# static priority: waves 4-7 at prio 1 for the whole K-loop in MLP-up and residual GEMMs, per-phase s_setprio flips removed
# baseline (speedup 1.0000x reference)
; #define PG8_STAGE(bufoff, gbase, voff) do { _Pragma("unroll") for (int _i = 0; _i < 2; ++_i) \
;         __builtin_amdgcn_global_load_lds((const unsigned*)((const char*)(gbase) + (voff)[_i]), (LAS unsigned*)(lds + (bufoff) + ldsw + _i * 8192), 16, 0, 0); } while (0)
; #define PG8_LDA(dst, b, h) do { _Pragma("unroll") for (int m = 0; m < 4; ++m) _Pragma("unroll") for (int k = 0; k < 2; ++k) dst[m][k] = *(const LAS bf16x8*)(lds + PG8_SA(b, h) + aoff + m * 2048 + k * 1024); } while (0)
; #define PG8_LDB(dst, b, h) do { _Pragma("unroll") for (int n = 0; n < 2; ++n) _Pragma("unroll") for (int k = 0; k < 2; ++k) dst[n][k] = *(const LAS bf16x8*)(lds + PG8_SB(b, h) + boff + n * 2048 + k * 1024); } while (0)
; #define PG8_MMA(ai, bj, At, Bt) do { __builtin_amdgcn_s_setprio(1); _Pragma("unroll") for (int m = 0; m < 4; ++m) _Pragma("unroll") for (int n = 0; n < 2; ++n) _Pragma("unroll") for (int k = 0; k < 2; ++k) \
;         acc[ai][bj][m][n] = __builtin_amdgcn_mfma_f32_16x16x32_bf16(Bt[n][k], At[m][k], acc[ai][bj][m][n], 0, 0, 0); __builtin_amdgcn_s_setprio(0); } while (0)
; #define PG8_WAIT_V(n) asm volatile("s_waitcnt vmcnt(" #n ")" ::: "memory")
; #define PG8_WAIT_L(n) asm volatile("s_waitcnt lgkmcnt(" #n ")" ::: "memory")
; #define PG8_BAR __builtin_amdgcn_s_barrier()
; #define PG8_SCHED __builtin_amdgcn_sched_barrier(0)
;     ...
;         const bool has_next = S.next(ui + 1, nxt);
;         const char* nA = has_next ? oa.base + (size_t)nxt.pm * oa.tstep : cA; const char* nA2 = has_next ? oa.base2 + (size_t)nxt.pm * oa.tstep : cA2; const char* nB = has_next ? ob.base + (size_t)nxt.pn * ob.tstep : cB;
; #pragma nounroll
;         for (int t = 0; t < nt; t += 2) {
;             const bool last = (t == nt - 2);
;             const char* a1 = PG8_ATILE(cA, cA2, t + 1);
;             const char* a2 = last ? nA : PG8_ATILE(cA, cA2, t + 2); const char* b2 = last ? nB : cB + (size_t)(t + 2) * 128;
;             const char* a3 = last ? nA + kA1 : PG8_ATILE(cA, cA2, t + 3); const char* b3 = b2 + kB1;
;             if constexpr (SP2) {
;             PG8_LDB(B0, 0, 0); PG8_LDB(B1, 0, 1); PG8_SCHED; PG8_LDA(At, 0, 0); PG8_STAGE(PG8_SA(1, 1), a1 + hA, voffA);
;             PG8_WAIT_V(8); PG8_WAIT_L(0); PG8_BAR; PG8_MMA(0, 0, At, B0); PG8_MMA(0, 1, At, B1); PG8_BAR; PG8_SCHED;
.LBB0_298:
	s_ashr_i32 s29, s28, 31
	s_lshl_b64 s[30:31], s[28:29], 19
	s_add_u32 s30, s46, s30
	s_addc_u32 s31, s47, s31
	s_and_b64 s[34:35], s[40:41], exec
	s_cselect_b32 s3, s31, s45
	s_cselect_b32 s29, s30, s44
	s_ashr_i32 s27, s26, 31
	s_lshl_b64 s[34:35], s[26:27], 19
	s_add_u32 s34, s1, s34
	s_addc_u32 s35, s4, s35
	s_and_b64 s[54:55], s[40:41], exec
	s_cselect_b32 s27, s35, s53
	s_cselect_b32 s54, s34, s52
	s_add_u32 s55, s29, 0x80
	s_addc_u32 s78, s3, 0
	s_add_u32 s79, s52, 0x100
	s_addc_u32 s80, s53, 0
	s_add_u32 s52, s44, 0x40080
	s_addc_u32 s53, s45, 0
	v_mov_b32_e32 v0, 0
	v_lshl_add_u64 v[128:129], s[52:53], 0, v[172:173]
	v_lshl_add_u64 v[130:131], s[52:53], 0, v[174:175]
	s_mov_b32 s81, -2
	s_mov_b64 s[52:53], 0
	v_mov_b32_e32 v1, v0
	v_mov_b32_e32 v2, v0
	v_mov_b32_e32 v3, v0
	v_mov_b32_e32 v4, v0
	v_mov_b32_e32 v5, v0
	v_mov_b32_e32 v6, v0
	v_mov_b32_e32 v7, v0
	v_mov_b32_e32 v16, v0
	v_mov_b32_e32 v17, v0
	v_mov_b32_e32 v18, v0
	v_mov_b32_e32 v19, v0
	v_mov_b32_e32 v20, v0
	v_mov_b32_e32 v21, v0
	v_mov_b32_e32 v22, v0
	v_mov_b32_e32 v23, v0
	v_mov_b32_e32 v32, v0
	v_mov_b32_e32 v33, v0
	v_mov_b32_e32 v34, v0
	v_mov_b32_e32 v35, v0
	v_mov_b32_e32 v36, v0
	v_mov_b32_e32 v37, v0
	v_mov_b32_e32 v38, v0
	v_mov_b32_e32 v39, v0
	v_mov_b32_e32 v48, v0
	v_mov_b32_e32 v49, v0
	v_mov_b32_e32 v50, v0
	v_mov_b32_e32 v51, v0
	v_mov_b32_e32 v52, v0
	v_mov_b32_e32 v53, v0
	v_mov_b32_e32 v54, v0
	v_mov_b32_e32 v55, v0
	v_mov_b32_e32 v8, v0
	v_mov_b32_e32 v9, v0
	v_mov_b32_e32 v10, v0
	v_mov_b32_e32 v11, v0
	v_mov_b32_e32 v12, v0
	v_mov_b32_e32 v13, v0
	v_mov_b32_e32 v14, v0
	v_mov_b32_e32 v15, v0
	v_mov_b32_e32 v24, v0
	v_mov_b32_e32 v25, v0
	v_mov_b32_e32 v26, v0
	v_mov_b32_e32 v27, v0
	v_mov_b32_e32 v28, v0
	v_mov_b32_e32 v29, v0
	v_mov_b32_e32 v30, v0
	v_mov_b32_e32 v31, v0
	v_mov_b32_e32 v40, v0
	v_mov_b32_e32 v41, v0
	v_mov_b32_e32 v42, v0
	v_mov_b32_e32 v43, v0
	v_mov_b32_e32 v44, v0
	v_mov_b32_e32 v45, v0
	v_mov_b32_e32 v46, v0
	v_mov_b32_e32 v47, v0
	v_mov_b32_e32 v56, v0
	v_mov_b32_e32 v57, v0
	v_mov_b32_e32 v58, v0
	v_mov_b32_e32 v59, v0
	v_mov_b32_e32 v60, v0
	v_mov_b32_e32 v61, v0
	v_mov_b32_e32 v62, v0
	v_mov_b32_e32 v63, v0
	v_mov_b32_e32 v64, v0
	v_mov_b32_e32 v65, v0
	v_mov_b32_e32 v66, v0
	v_mov_b32_e32 v67, v0
	v_mov_b32_e32 v68, v0
	v_mov_b32_e32 v69, v0
	v_mov_b32_e32 v70, v0
	v_mov_b32_e32 v71, v0
	v_mov_b32_e32 v80, v0
	v_mov_b32_e32 v81, v0
	v_mov_b32_e32 v82, v0
	v_mov_b32_e32 v83, v0
	v_mov_b32_e32 v84, v0
	v_mov_b32_e32 v85, v0
	v_mov_b32_e32 v86, v0
	v_mov_b32_e32 v87, v0
	v_mov_b32_e32 v96, v0
	v_mov_b32_e32 v97, v0
	v_mov_b32_e32 v98, v0
	v_mov_b32_e32 v99, v0
	v_mov_b32_e32 v100, v0
	v_mov_b32_e32 v101, v0
	v_mov_b32_e32 v102, v0
	v_mov_b32_e32 v103, v0
	v_mov_b32_e32 v112, v0
	v_mov_b32_e32 v113, v0
	v_mov_b32_e32 v114, v0
	v_mov_b32_e32 v115, v0
	v_mov_b32_e32 v116, v0
	v_mov_b32_e32 v117, v0
	v_mov_b32_e32 v118, v0
	v_mov_b32_e32 v119, v0
	v_mov_b32_e32 v72, v0
	v_mov_b32_e32 v73, v0
	v_mov_b32_e32 v74, v0
	v_mov_b32_e32 v75, v0
	v_mov_b32_e32 v76, v0
	v_mov_b32_e32 v77, v0
	v_mov_b32_e32 v78, v0
	v_mov_b32_e32 v79, v0
	v_mov_b32_e32 v88, v0
	v_mov_b32_e32 v89, v0
	v_mov_b32_e32 v90, v0
	v_mov_b32_e32 v91, v0
	v_mov_b32_e32 v92, v0
	v_mov_b32_e32 v93, v0
	v_mov_b32_e32 v94, v0
	v_mov_b32_e32 v95, v0
	v_mov_b32_e32 v104, v0
	v_mov_b32_e32 v105, v0
	v_mov_b32_e32 v106, v0
	v_mov_b32_e32 v107, v0
	v_mov_b32_e32 v108, v0
	v_mov_b32_e32 v109, v0
	v_mov_b32_e32 v110, v0
	v_mov_b32_e32 v111, v0
	v_mov_b32_e32 v120, v0
	v_mov_b32_e32 v121, v0
	v_mov_b32_e32 v122, v0
	v_mov_b32_e32 v123, v0
	v_mov_b32_e32 v124, v0
	v_mov_b32_e32 v125, v0
	v_mov_b32_e32 v126, v0
	v_mov_b32_e32 v127, v0
	s_setprio 0
	s_cmp_lg_u64 s[14:15], 0
	s_cbranch_scc0 .Lprio_up
	s_setprio 1
.Lprio_up:
.LBB0_299:
	s_add_u32 s72, s44, s52
	s_addc_u32 s73, s45, s53
	s_add_u32 s98, s72, 0x40080
	s_addc_u32 s99, s73, 0
	s_add_u32 s76, s72, 0x100
	s_addc_u32 s77, s73, 0
	s_add_u32 s74, s79, s52
	s_addc_u32 s75, s80, s53
	s_add_u32 s72, s72, 0x180
	s_addc_u32 s73, s73, 0
	s_add_i32 s82, 0, 0x10000
	s_add_i32 s89, 0, 0x14000
	v_add_u32_e32 v144, s82, v193
	v_add_u32_e32 v184, s89, v193
	ds_read_b128 v[132:135], v144
	ds_read_b128 v[136:139], v144 offset:1024
	ds_read_b128 v[140:143], v144 offset:2048
	ds_read_b128 v[144:147], v144 offset:3072
	ds_read_b128 v[148:151], v184
	ds_read_b128 v[176:179], v184 offset:1024
	ds_read_b128 v[180:183], v184 offset:2048
	ds_read_b128 v[184:187], v184 offset:3072
	s_cmpk_eq_i32 s52, 0x700
	s_cselect_b32 s73, s78, s73
	s_cselect_b32 s72, s55, s72
	s_cselect_b32 s75, s27, s75
	s_cselect_b32 s74, s54, s74
	s_cselect_b32 s77, s3, s77
	s_cselect_b32 s76, s29, s76
	s_add_i32 m0, s6, 0xc000
	ds_read_b128 v[188:191], v198
	ds_read_b128 v[200:203], v198 offset:1024
	ds_read_b128 v[208:211], v198 offset:2048
	ds_read_b128 v[214:217], v198 offset:3072
	ds_read_b128 v[230:233], v198 offset:4096
	ds_read_b128 v[234:237], v198 offset:5120
	ds_read_b128 v[238:241], v198 offset:6144
	ds_read_b128 v[242:245], v198 offset:7168
	global_load_lds_dwordx4 v172, s[98:99]
	s_add_i32 m0, s6, 0xe000
	s_nop 0
	global_load_lds_dwordx4 v174, s[98:99]
	s_waitcnt vmcnt(8)
	s_waitcnt lgkmcnt(0)
	s_barrier
; #define PG8_STAGE(bufoff, gbase, voff) do { _Pragma("unroll") for (int _i = 0; _i < 2; ++_i) \
;         __builtin_amdgcn_global_load_lds((const unsigned*)((const char*)(gbase) + (voff)[_i]), (LAS unsigned*)(lds + (bufoff) + ldsw + _i * 8192), 16, 0, 0); } while (0)
; #define PG8_LDA(dst, b, h) do { _Pragma("unroll") for (int m = 0; m < 4; ++m) _Pragma("unroll") for (int k = 0; k < 2; ++k) dst[m][k] = *(const LAS bf16x8*)(lds + PG8_SA(b, h) + aoff + m * 2048 + k * 1024); } while (0)
; #define PG8_LDB(dst, b, h) do { _Pragma("unroll") for (int n = 0; n < 2; ++n) _Pragma("unroll") for (int k = 0; k < 2; ++k) dst[n][k] = *(const LAS bf16x8*)(lds + PG8_SB(b, h) + boff + n * 2048 + k * 1024); } while (0)
; #define PG8_MMA(ai, bj, At, Bt) do { __builtin_amdgcn_s_setprio(1); _Pragma("unroll") for (int m = 0; m < 4; ++m) _Pragma("unroll") for (int n = 0; n < 2; ++n) _Pragma("unroll") for (int k = 0; k < 2; ++k) \
;         acc[ai][bj][m][n] = __builtin_amdgcn_mfma_f32_16x16x32_bf16(Bt[n][k], At[m][k], acc[ai][bj][m][n], 0, 0, 0); __builtin_amdgcn_s_setprio(0); } while (0)
; #define PG8_WAIT_V(n) asm volatile("s_waitcnt vmcnt(" #n ")" ::: "memory")
; #define PG8_WAIT_L(n) asm volatile("s_waitcnt lgkmcnt(" #n ")" ::: "memory")
; #define PG8_BAR __builtin_amdgcn_s_barrier()
; #define PG8_SCHED __builtin_amdgcn_sched_barrier(0)
;     ...
;             PG8_WAIT_V(8); PG8_WAIT_L(0); PG8_BAR; PG8_MMA(0, 0, At, B0); PG8_MMA(0, 1, At, B1); PG8_BAR; PG8_SCHED;
;             PG8_LDA(At, 0, 1); PG8_STAGE(PG8_SB(0, 0), b2, voffB); PG8_STAGE(PG8_SB(0, 1), b2 + hB, voffB); PG8_STAGE(PG8_SA(0, 0), a2, voffA);
;             PG8_WAIT_V(8); PG8_WAIT_L(0); PG8_BAR; PG8_MMA(1, 0, At, B0); PG8_MMA(1, 1, At, B1); PG8_BAR; PG8_SCHED;
;             PG8_LDB(B0, 1, 0); PG8_LDB(B1, 1, 1); PG8_SCHED; PG8_LDA(At, 1, 0); PG8_STAGE(PG8_SA(0, 1), a2 + hA, voffA);
;             PG8_WAIT_V(8); PG8_WAIT_L(0); PG8_BAR; PG8_MMA(0, 0, At, B0); PG8_MMA(0, 1, At, B1); PG8_BAR; PG8_SCHED;
;             PG8_LDA(At, 1, 1); PG8_STAGE(PG8_SB(1, 0), b3, voffB); PG8_STAGE(PG8_SB(1, 1), b3 + hB, voffB); PG8_STAGE(PG8_SA(1, 0), a3, voffA);
	s_waitcnt lgkmcnt(0)
	v_mfma_f32_16x16x32_bf16 v[124:127], v[132:135], v[188:191], v[124:127]
	v_mfma_f32_16x16x32_bf16 v[124:127], v[136:139], v[200:203], v[124:127]
	v_mfma_f32_16x16x32_bf16 v[120:123], v[144:147], v[200:203], v[120:123]
	v_mfma_f32_16x16x32_bf16 v[120:123], v[140:143], v[188:191], v[120:123]
	v_mfma_f32_16x16x32_bf16 v[104:107], v[140:143], v[208:211], v[104:107]
	v_mfma_f32_16x16x32_bf16 v[104:107], v[144:147], v[214:217], v[104:107]
	v_mfma_f32_16x16x32_bf16 v[108:111], v[136:139], v[214:217], v[108:111]
	v_mfma_f32_16x16x32_bf16 v[108:111], v[132:135], v[208:211], v[108:111]
	v_mfma_f32_16x16x32_bf16 v[92:95], v[132:135], v[230:233], v[92:95]
	v_mfma_f32_16x16x32_bf16 v[92:95], v[136:139], v[234:237], v[92:95]
	v_mfma_f32_16x16x32_bf16 v[88:91], v[144:147], v[234:237], v[88:91]
	v_mfma_f32_16x16x32_bf16 v[88:91], v[140:143], v[230:233], v[88:91]
	v_mfma_f32_16x16x32_bf16 v[72:75], v[140:143], v[238:241], v[72:75]
	v_mfma_f32_16x16x32_bf16 v[72:75], v[144:147], v[242:245], v[72:75]
	v_mfma_f32_16x16x32_bf16 v[76:79], v[136:139], v[242:245], v[76:79]
	v_mfma_f32_16x16x32_bf16 v[76:79], v[132:135], v[238:241], v[76:79]
	v_mfma_f32_16x16x32_bf16 v[116:119], v[148:151], v[188:191], v[116:119]
	v_mfma_f32_16x16x32_bf16 v[116:119], v[176:179], v[200:203], v[116:119]
	v_mfma_f32_16x16x32_bf16 v[112:115], v[184:187], v[200:203], v[112:115]
	v_mfma_f32_16x16x32_bf16 v[112:115], v[180:183], v[188:191], v[112:115]
	v_mfma_f32_16x16x32_bf16 v[96:99], v[180:183], v[208:211], v[96:99]
	v_mfma_f32_16x16x32_bf16 v[96:99], v[184:187], v[214:217], v[96:99]
	v_mfma_f32_16x16x32_bf16 v[100:103], v[176:179], v[214:217], v[100:103]
	v_mfma_f32_16x16x32_bf16 v[100:103], v[148:151], v[208:211], v[100:103]
	v_mfma_f32_16x16x32_bf16 v[84:87], v[148:151], v[230:233], v[84:87]
	v_mfma_f32_16x16x32_bf16 v[84:87], v[176:179], v[234:237], v[84:87]
	v_mfma_f32_16x16x32_bf16 v[80:83], v[184:187], v[234:237], v[80:83]
	v_mfma_f32_16x16x32_bf16 v[80:83], v[180:183], v[230:233], v[80:83]
	v_mfma_f32_16x16x32_bf16 v[64:67], v[180:183], v[238:241], v[64:67]
	v_mfma_f32_16x16x32_bf16 v[64:67], v[184:187], v[242:245], v[64:67]
	v_mfma_f32_16x16x32_bf16 v[68:71], v[176:179], v[242:245], v[68:71]
	v_mfma_f32_16x16x32_bf16 v[68:71], v[148:151], v[238:241], v[68:71]
	s_barrier
	s_add_i32 s82, s82, s5
	s_mov_b32 m0, s82
	ds_read_b128 v[188:191], v198 offset:16384
	ds_read_b128 v[200:203], v198 offset:17408
	ds_read_b128 v[208:211], v198 offset:18432
	ds_read_b128 v[214:217], v198 offset:19456
	ds_read_b128 v[230:233], v198 offset:20480
	ds_read_b128 v[234:237], v198 offset:21504
	ds_read_b128 v[238:241], v198 offset:22528
	ds_read_b128 v[242:245], v198 offset:23552
	global_load_lds_dwordx4 v156, s[74:75]
	s_add_i32 m0, s82, 0x2000
	s_add_u32 s82, s74, 0x40000
	s_addc_u32 s83, s75, 0
	s_add_i32 s89, s89, s5
	global_load_lds_dwordx4 v168, s[74:75]
	s_mov_b32 m0, s89
	s_nop 0
	global_load_lds_dwordx4 v156, s[82:83]
	s_add_i32 m0, s89, 0x2000
	s_nop 0
	global_load_lds_dwordx4 v168, s[82:83]
	s_mov_b32 m0, s6
	s_nop 0
	global_load_lds_dwordx4 v152, s[76:77]
	s_mov_b32 m0, s7
	s_nop 0
	global_load_lds_dwordx4 v154, s[76:77]
	s_waitcnt vmcnt(8)
	s_waitcnt lgkmcnt(0)
	s_barrier
	s_waitcnt lgkmcnt(0)
	v_mfma_f32_16x16x32_bf16 v[60:63], v[132:135], v[188:191], v[60:63]
	v_mfma_f32_16x16x32_bf16 v[60:63], v[136:139], v[200:203], v[60:63]
	v_mfma_f32_16x16x32_bf16 v[56:59], v[144:147], v[200:203], v[56:59]
	v_mfma_f32_16x16x32_bf16 v[56:59], v[140:143], v[188:191], v[56:59]
	v_mfma_f32_16x16x32_bf16 v[40:43], v[140:143], v[208:211], v[40:43]
	v_mfma_f32_16x16x32_bf16 v[40:43], v[144:147], v[214:217], v[40:43]
	v_mfma_f32_16x16x32_bf16 v[44:47], v[136:139], v[214:217], v[44:47]
	v_mfma_f32_16x16x32_bf16 v[44:47], v[132:135], v[208:211], v[44:47]
	v_mfma_f32_16x16x32_bf16 v[28:31], v[132:135], v[230:233], v[28:31]
	v_mfma_f32_16x16x32_bf16 v[28:31], v[136:139], v[234:237], v[28:31]
	v_mfma_f32_16x16x32_bf16 v[24:27], v[144:147], v[234:237], v[24:27]
	v_mfma_f32_16x16x32_bf16 v[24:27], v[140:143], v[230:233], v[24:27]
	v_mfma_f32_16x16x32_bf16 v[8:11], v[140:143], v[238:241], v[8:11]
	v_mfma_f32_16x16x32_bf16 v[8:11], v[144:147], v[242:245], v[8:11]
	v_mfma_f32_16x16x32_bf16 v[12:15], v[136:139], v[242:245], v[12:15]
	v_mfma_f32_16x16x32_bf16 v[12:15], v[132:135], v[238:241], v[12:15]
	v_mfma_f32_16x16x32_bf16 v[52:55], v[148:151], v[188:191], v[52:55]
	v_mfma_f32_16x16x32_bf16 v[52:55], v[176:179], v[200:203], v[52:55]
	v_mfma_f32_16x16x32_bf16 v[48:51], v[184:187], v[200:203], v[48:51]
	v_mfma_f32_16x16x32_bf16 v[48:51], v[180:183], v[188:191], v[48:51]
	v_mfma_f32_16x16x32_bf16 v[32:35], v[180:183], v[208:211], v[32:35]
	v_mfma_f32_16x16x32_bf16 v[32:35], v[184:187], v[214:217], v[32:35]
	v_mfma_f32_16x16x32_bf16 v[36:39], v[176:179], v[214:217], v[36:39]
	v_mfma_f32_16x16x32_bf16 v[36:39], v[148:151], v[208:211], v[36:39]
	v_mfma_f32_16x16x32_bf16 v[20:23], v[148:151], v[230:233], v[20:23]
	v_mfma_f32_16x16x32_bf16 v[20:23], v[176:179], v[234:237], v[20:23]
	v_mfma_f32_16x16x32_bf16 v[16:19], v[184:187], v[234:237], v[16:19]
	v_mfma_f32_16x16x32_bf16 v[16:19], v[180:183], v[230:233], v[16:19]
	v_mfma_f32_16x16x32_bf16 v[0:3], v[180:183], v[238:241], v[0:3]
	v_mfma_f32_16x16x32_bf16 v[0:3], v[184:187], v[242:245], v[0:3]
	v_mfma_f32_16x16x32_bf16 v[4:7], v[176:179], v[242:245], v[4:7]
	v_mfma_f32_16x16x32_bf16 v[4:7], v[148:151], v[238:241], v[4:7]
	s_barrier
; #define PG8_STAGE(bufoff, gbase, voff) do { _Pragma("unroll") for (int _i = 0; _i < 2; ++_i) \
;         __builtin_amdgcn_global_load_lds((const unsigned*)((const char*)(gbase) + (voff)[_i]), (LAS unsigned*)(lds + (bufoff) + ldsw + _i * 8192), 16, 0, 0); } while (0)
; #define PG8_LDA(dst, b, h) do { _Pragma("unroll") for (int m = 0; m < 4; ++m) _Pragma("unroll") for (int k = 0; k < 2; ++k) dst[m][k] = *(const LAS bf16x8*)(lds + PG8_SA(b, h) + aoff + m * 2048 + k * 1024); } while (0)
; #define PG8_BAR __builtin_amdgcn_s_barrier()
;     ...
;             PG8_LDB(B0, 1, 0); PG8_LDB(B1, 1, 1); PG8_SCHED; PG8_LDA(At, 1, 0); PG8_STAGE(PG8_SA(0, 1), a2 + hA, voffA);
;             PG8_WAIT_V(8); PG8_WAIT_L(0); PG8_BAR; PG8_MMA(0, 0, At, B0); PG8_MMA(0, 1, At, B1); PG8_BAR; PG8_SCHED;
;             PG8_LDA(At, 1, 1); PG8_STAGE(PG8_SB(1, 0), b3, voffB); PG8_STAGE(PG8_SB(1, 1), b3 + hB, voffB); PG8_STAGE(PG8_SA(1, 0), a3, voffA);
;             PG8_WAIT_V(8); PG8_WAIT_L(0); PG8_BAR; PG8_MMA(1, 0, At, B0); PG8_MMA(1, 1, At, B1); PG8_BAR; PG8_SCHED;
;             } else {
;             PG8_LDB(B0, 0, 0); PG8_SCHED; PG8_LDA(At, 0, 0); PG8_STAGE(PG8_SA(1, 1), a1 + hA, voffA);
;             PG8_WAIT_L(8); PG8_BAR; PG8_WAIT_L(0); PG8_MMA(0, 0, At, B0); PG8_BAR; PG8_SCHED;
;             PG8_LDB(B1, 0, 1); PG8_STAGE(PG8_SB(0, 0), b2, voffB);
;             PG8_BAR; PG8_WAIT_L(0); PG8_MMA(0, 1, At, B1); PG8_BAR;
;             PG8_LDA(At, 0, 1); PG8_STAGE(PG8_SA(0, 0), a2, voffA);
;             PG8_BAR; PG8_WAIT_L(0); PG8_MMA(1, 0, At, B0); PG8_BAR; PG8_SCHED;
;             PG8_STAGE(PG8_SB(0, 1), b2 + hB, voffB);
;             PG8_WAIT_V(6); PG8_BAR; PG8_MMA(1, 1, At, B1); PG8_BAR;
;             PG8_LDB(B0, 1, 0); PG8_SCHED; PG8_LDA(At, 1, 0); PG8_STAGE(PG8_SA(0, 1), a2 + hA, voffA);
;             PG8_WAIT_L(8); PG8_BAR; PG8_WAIT_L(0); PG8_MMA(0, 0, At, B0); PG8_BAR; PG8_SCHED;
;             PG8_LDB(B1, 1, 1); PG8_STAGE(PG8_SB(1, 0), b3, voffB);
;             PG8_BAR; PG8_WAIT_L(0); PG8_MMA(0, 1, At, B1); PG8_BAR;
;             PG8_LDA(At, 1, 1); PG8_STAGE(PG8_SA(1, 0), a3, voffA);
;             PG8_BAR; PG8_WAIT_L(0); PG8_MMA(1, 0, At, B0); PG8_BAR; PG8_SCHED;
;             PG8_STAGE(PG8_SB(1, 1), b3 + hB, voffB);
;             PG8_WAIT_V(6); PG8_BAR; PG8_MMA(1, 1, At, B1); PG8_BAR;
;             }
;         }
;         if constexpr (ALIGN_EPI) { if (wr == 0) PG8_BAR; }
	s_add_i32 s82, 0, 0x18000
	s_add_i32 s83, 0, 0x1c000
	v_add_u32_e32 v144, s82, v193
	v_add_u32_e32 v184, s83, v193
	ds_read_b128 v[132:135], v144
	ds_read_b128 v[136:139], v144 offset:1024
	ds_read_b128 v[140:143], v144 offset:2048
	ds_read_b128 v[144:147], v144 offset:3072
	ds_read_b128 v[148:151], v184
	ds_read_b128 v[176:179], v184 offset:1024
	ds_read_b128 v[180:183], v184 offset:2048
	ds_read_b128 v[184:187], v184 offset:3072
	s_add_u32 s76, s76, 0x40000
	s_addc_u32 s77, s77, 0
	s_mov_b32 m0, s8
	ds_read_b128 v[188:191], v198 offset:32768
	ds_read_b128 v[200:203], v198 offset:33792
	ds_read_b128 v[208:211], v198 offset:34816
	ds_read_b128 v[214:217], v198 offset:35840
	ds_read_b128 v[230:233], v198 offset:36864
	ds_read_b128 v[234:237], v198 offset:37888
	ds_read_b128 v[238:241], v198 offset:38912
	ds_read_b128 v[242:245], v198 offset:39936
	global_load_lds_dwordx4 v152, s[76:77]
	s_mov_b32 m0, s9
	s_nop 0
	global_load_lds_dwordx4 v154, s[76:77]
	s_waitcnt vmcnt(8)
	s_waitcnt lgkmcnt(0)
	s_barrier
	s_waitcnt lgkmcnt(0)
	v_mfma_f32_16x16x32_bf16 v[124:127], v[132:135], v[188:191], v[124:127]
	v_mfma_f32_16x16x32_bf16 v[124:127], v[136:139], v[200:203], v[124:127]
	v_mfma_f32_16x16x32_bf16 v[120:123], v[144:147], v[200:203], v[120:123]
	v_mfma_f32_16x16x32_bf16 v[120:123], v[140:143], v[188:191], v[120:123]
	v_mfma_f32_16x16x32_bf16 v[104:107], v[140:143], v[208:211], v[104:107]
	v_mfma_f32_16x16x32_bf16 v[104:107], v[144:147], v[214:217], v[104:107]
	v_mfma_f32_16x16x32_bf16 v[108:111], v[136:139], v[214:217], v[108:111]
	v_mfma_f32_16x16x32_bf16 v[108:111], v[132:135], v[208:211], v[108:111]
	v_mfma_f32_16x16x32_bf16 v[92:95], v[132:135], v[230:233], v[92:95]
	v_mfma_f32_16x16x32_bf16 v[92:95], v[136:139], v[234:237], v[92:95]
	v_mfma_f32_16x16x32_bf16 v[88:91], v[144:147], v[234:237], v[88:91]
	v_mfma_f32_16x16x32_bf16 v[88:91], v[140:143], v[230:233], v[88:91]
	v_mfma_f32_16x16x32_bf16 v[72:75], v[140:143], v[238:241], v[72:75]
	v_mfma_f32_16x16x32_bf16 v[72:75], v[144:147], v[242:245], v[72:75]
	v_mfma_f32_16x16x32_bf16 v[76:79], v[136:139], v[242:245], v[76:79]
	v_mfma_f32_16x16x32_bf16 v[76:79], v[132:135], v[238:241], v[76:79]
	v_mfma_f32_16x16x32_bf16 v[116:119], v[148:151], v[188:191], v[116:119]
	v_mfma_f32_16x16x32_bf16 v[116:119], v[176:179], v[200:203], v[116:119]
	v_mfma_f32_16x16x32_bf16 v[112:115], v[184:187], v[200:203], v[112:115]
	v_mfma_f32_16x16x32_bf16 v[112:115], v[180:183], v[188:191], v[112:115]
	v_mfma_f32_16x16x32_bf16 v[96:99], v[180:183], v[208:211], v[96:99]
	v_mfma_f32_16x16x32_bf16 v[96:99], v[184:187], v[214:217], v[96:99]
	v_mfma_f32_16x16x32_bf16 v[100:103], v[176:179], v[214:217], v[100:103]
	v_mfma_f32_16x16x32_bf16 v[100:103], v[148:151], v[208:211], v[100:103]
	v_mfma_f32_16x16x32_bf16 v[84:87], v[148:151], v[230:233], v[84:87]
	v_mfma_f32_16x16x32_bf16 v[84:87], v[176:179], v[234:237], v[84:87]
	v_mfma_f32_16x16x32_bf16 v[80:83], v[184:187], v[234:237], v[80:83]
	v_mfma_f32_16x16x32_bf16 v[80:83], v[180:183], v[230:233], v[80:83]
	v_mfma_f32_16x16x32_bf16 v[64:67], v[180:183], v[238:241], v[64:67]
	v_mfma_f32_16x16x32_bf16 v[64:67], v[184:187], v[242:245], v[64:67]
	v_mfma_f32_16x16x32_bf16 v[68:71], v[176:179], v[242:245], v[68:71]
	v_mfma_f32_16x16x32_bf16 v[68:71], v[148:151], v[238:241], v[68:71]
	s_barrier
	s_add_i32 s76, s82, s5
	s_add_u32 s100, s74, s38
	s_addc_u32 s101, s75, s39
	s_mov_b32 m0, s76
	ds_read_b128 v[188:191], v198 offset:49152
	ds_read_b128 v[200:203], v198 offset:50176
	ds_read_b128 v[208:211], v198 offset:51200
	ds_read_b128 v[214:217], v198 offset:52224
	ds_read_b128 v[230:233], v198 offset:53248
	ds_read_b128 v[234:237], v198 offset:54272
	ds_read_b128 v[238:241], v198 offset:55296
	ds_read_b128 v[242:245], v198 offset:56320
	global_load_lds_dwordx4 v156, s[100:101]
	s_add_i32 m0, s76, 0x2000
	s_add_u32 s74, s74, 0x40080
	s_addc_u32 s75, s75, 0
	s_add_i32 s76, s83, s5
	global_load_lds_dwordx4 v168, s[100:101]
	s_mov_b32 m0, s76
	s_nop 0
	global_load_lds_dwordx4 v156, s[74:75]
	s_add_i32 m0, s76, 0x2000
	s_nop 0
	global_load_lds_dwordx4 v168, s[74:75]
	s_mov_b32 m0, s36
	s_nop 0
	global_load_lds_dwordx4 v152, s[72:73]
	s_mov_b32 m0, s42
	s_nop 0
	global_load_lds_dwordx4 v154, s[72:73]
	s_waitcnt vmcnt(8)
	s_waitcnt lgkmcnt(0)
	s_barrier
	s_waitcnt lgkmcnt(0)
	v_mfma_f32_16x16x32_bf16 v[60:63], v[132:135], v[188:191], v[60:63]
	v_mfma_f32_16x16x32_bf16 v[60:63], v[136:139], v[200:203], v[60:63]
	v_mfma_f32_16x16x32_bf16 v[56:59], v[144:147], v[200:203], v[56:59]
	v_mfma_f32_16x16x32_bf16 v[56:59], v[140:143], v[188:191], v[56:59]
	v_mfma_f32_16x16x32_bf16 v[40:43], v[140:143], v[208:211], v[40:43]
	v_mfma_f32_16x16x32_bf16 v[40:43], v[144:147], v[214:217], v[40:43]
	v_mfma_f32_16x16x32_bf16 v[44:47], v[136:139], v[214:217], v[44:47]
	v_mfma_f32_16x16x32_bf16 v[44:47], v[132:135], v[208:211], v[44:47]
	v_mfma_f32_16x16x32_bf16 v[28:31], v[132:135], v[230:233], v[28:31]
	v_mfma_f32_16x16x32_bf16 v[28:31], v[136:139], v[234:237], v[28:31]
	v_mfma_f32_16x16x32_bf16 v[24:27], v[144:147], v[234:237], v[24:27]
	v_mfma_f32_16x16x32_bf16 v[24:27], v[140:143], v[230:233], v[24:27]
	v_mfma_f32_16x16x32_bf16 v[8:11], v[140:143], v[238:241], v[8:11]
	v_mfma_f32_16x16x32_bf16 v[8:11], v[144:147], v[242:245], v[8:11]
	v_mfma_f32_16x16x32_bf16 v[12:15], v[136:139], v[242:245], v[12:15]
	v_mfma_f32_16x16x32_bf16 v[12:15], v[132:135], v[238:241], v[12:15]
	v_mfma_f32_16x16x32_bf16 v[52:55], v[148:151], v[188:191], v[52:55]
	v_mfma_f32_16x16x32_bf16 v[52:55], v[176:179], v[200:203], v[52:55]
	v_mfma_f32_16x16x32_bf16 v[48:51], v[184:187], v[200:203], v[48:51]
	v_mfma_f32_16x16x32_bf16 v[48:51], v[180:183], v[188:191], v[48:51]
	v_mfma_f32_16x16x32_bf16 v[32:35], v[180:183], v[208:211], v[32:35]
	v_mfma_f32_16x16x32_bf16 v[32:35], v[184:187], v[214:217], v[32:35]
	v_mfma_f32_16x16x32_bf16 v[36:39], v[176:179], v[214:217], v[36:39]
	v_mfma_f32_16x16x32_bf16 v[36:39], v[148:151], v[208:211], v[36:39]
	v_mfma_f32_16x16x32_bf16 v[20:23], v[148:151], v[230:233], v[20:23]
	v_mfma_f32_16x16x32_bf16 v[20:23], v[176:179], v[234:237], v[20:23]
	v_mfma_f32_16x16x32_bf16 v[16:19], v[184:187], v[234:237], v[16:19]
	v_mfma_f32_16x16x32_bf16 v[16:19], v[180:183], v[230:233], v[16:19]
	v_mfma_f32_16x16x32_bf16 v[0:3], v[180:183], v[238:241], v[0:3]
	v_mfma_f32_16x16x32_bf16 v[0:3], v[184:187], v[242:245], v[0:3]
	v_mfma_f32_16x16x32_bf16 v[4:7], v[176:179], v[242:245], v[4:7]
	v_mfma_f32_16x16x32_bf16 v[4:7], v[148:151], v[238:241], v[4:7]
	s_barrier
	s_add_i32 s81, s81, 2
	s_add_u32 s52, s52, 0x100
	s_addc_u32 s53, s53, 0
	s_cmp_gt_u32 s81, 13
	s_cbranch_scc0 .LBB0_299
	s_and_b64 vcc, exec, s[16:17]
	s_cbranch_vccz .LBB0_302
	s_barrier
; __device__ __forceinline__ float red4(float s) {
;     { auto rr = __builtin_amdgcn_permlane16_swap(__float_as_uint(s), __float_as_uint(s), false, false); s = __uint_as_float(rr[0]) + __uint_as_float(rr[1]); }
;     { auto rr = __builtin_amdgcn_permlane32_swap(__float_as_uint(s), __float_as_uint(s), false, false); s = __uint_as_float(rr[0]) + __uint_as_float(rr[1]); }
;     return s; }
;     __device__ __forceinline__ void operator()(EPI_ARGS) const {
;         const int row0 = u.om * BM + wr * 64 + fr, col0 = u.on * BM + wc * 32 + 8 * fq;
;         float rs[2][4];
;         { f32x4 pa[2][4];
; #pragma unroll
;           for (int ai = 0; ai < 2; ++ai)
; #pragma unroll
;               for (int m = 0; m < 4; ++m) pa[ai][m] = gldf4(ss + (size_t)(row0 + ai * HALF + m * 16) * 16 + fq * 4);
; #pragma unroll
;           for (int ai = 0; ai < 2; ++ai)
; #pragma unroll
;               for (int m = 0; m < 4; ++m) rs[ai][m] = rsqrtf(red4((pa[ai][m][0] + pa[ai][m][1]) + (pa[ai][m][2] + pa[ai][m][3])) * (1.0f / 1024.0f) + EPS); }
; #pragma unroll
;         for (int ai = 0; ai < 2; ++ai)
; #pragma unroll
;             for (int m = 0; m < 4; ++m) { const int row = row0 + ai * HALF + m * 16; const float r = rs[ai][m];
; #pragma unroll
;                 for (int bj = 0; bj < 2; ++bj) { f32x4 v0 = acc[ai][bj][m][0] * r, v1 = acc[ai][bj][m][1] * r;
.LBB0_302:
	s_setprio 0
	v_lshl_add_u32 v190, s2, 8, v165
	v_ashrrev_i32_e32 v191, 31, v190
	v_lshlrev_b64 v[128:129], 6, v[190:191]
	v_or_b32_e32 v188, 16, v190
	v_lshl_add_u64 v[128:129], v[170:171], 0, v[128:129]
	v_ashrrev_i32_e32 v189, 31, v188
	global_load_dwordx4 v[200:203], v[128:129], off
	v_lshlrev_b64 v[128:129], 6, v[188:189]
	v_lshl_add_u64 v[128:129], v[170:171], 0, v[128:129]
	global_load_dwordx4 v[208:211], v[128:129], off
	v_or_b32_e32 v186, 32, v190
	v_ashrrev_i32_e32 v187, 31, v186
	v_lshlrev_b64 v[128:129], 6, v[186:187]
	v_or_b32_e32 v184, 48, v190
	v_lshl_add_u64 v[128:129], v[170:171], 0, v[128:129]
	v_ashrrev_i32_e32 v185, 31, v184
	global_load_dwordx4 v[148:151], v[128:129], off
	v_lshlrev_b64 v[128:129], 6, v[184:185]
	v_lshl_add_u64 v[128:129], v[170:171], 0, v[128:129]
	global_load_dwordx4 v[144:147], v[128:129], off
	v_add_u32_e32 v182, 0x80, v190
	v_ashrrev_i32_e32 v183, 31, v182
	v_lshlrev_b64 v[128:129], 6, v[182:183]
	v_add_u32_e32 v180, 0x90, v190
	v_lshl_add_u64 v[128:129], v[170:171], 0, v[128:129]
	v_ashrrev_i32_e32 v181, 31, v180
	global_load_dwordx4 v[140:143], v[128:129], off
	v_lshlrev_b64 v[128:129], 6, v[180:181]
	v_lshl_add_u64 v[128:129], v[170:171], 0, v[128:129]
	global_load_dwordx4 v[136:139], v[128:129], off
	v_add_u32_e32 v178, 0xa0, v190
	v_ashrrev_i32_e32 v179, 31, v178
	v_lshlrev_b64 v[128:129], 6, v[178:179]
	v_add_u32_e32 v176, 0xb0, v190
	v_lshl_add_u64 v[128:129], v[170:171], 0, v[128:129]
	v_ashrrev_i32_e32 v177, 31, v176
	global_load_dwordx4 v[132:135], v[128:129], off
	v_lshlrev_b64 v[128:129], 6, v[176:177]
	v_lshl_add_u64 v[128:129], v[170:171], 0, v[128:129]
	global_load_dwordx4 v[128:131], v[128:129], off
	s_mov_b32 s2, 0x358637bd
	s_mov_b32 s44, 0x3a800000
	s_mov_b32 s89, 0x800000
	s_waitcnt vmcnt(0)
	v_mov_b32_e32 v196, v201
	v_mov_b32_e32 v197, v202
	v_mov_b32_e32 v201, v203
	v_pk_add_f32 v[196:197], v[196:197], v[200:201]
	v_mov_b32_e32 v202, v209
	v_pk_add_f32 v[196:197], v[196:197], v[196:197] op_sel:[0,1] op_sel_hi:[1,0]
	v_mov_b32_e32 v203, v210
	v_mov_b32_e32 v209, v211
	v_mov_b32_e32 v192, v196
	v_pk_add_f32 v[202:203], v[202:203], v[208:209]
	s_nop 0
	v_permlane16_swap_b32_e32 v196, v192
	v_pk_add_f32 v[202:203], v[202:203], v[202:203] op_sel:[0,1] op_sel_hi:[1,0]
	v_add_f32_e32 v197, v196, v192
	v_mov_b32_e32 v192, v202
	s_nop 1
	v_permlane16_swap_b32_e32 v202, v192
	v_add_f32_e32 v196, v202, v192
	v_mov_b32_e32 v201, v197
	v_mov_b32_e32 v200, v196
	s_nop 0
	v_permlane32_swap_b32_e32 v197, v201
	v_permlane32_swap_b32_e32 v196, v200
	v_pk_add_f32 v[200:201], v[196:197], v[200:201]
	v_mov_b64_e32 v[196:197], s[2:3]
	v_pk_fma_f32 v[200:201], v[200:201], s[44:45], v[196:197] op_sel_hi:[1,0,0]
	s_nop 0
	v_mul_f32_e32 v192, 0x4b800000, v201
	v_cmp_gt_f32_e64 s[2:3], s89, v201
	v_cmp_gt_f32_e32 vcc, s89, v200
	s_nop 0
	v_cndmask_b32_e64 v192, v201, v192, s[2:3]
	v_rsq_f32_e32 v192, v192
	v_mov_b32_e32 v201, v150
	v_mul_f32_e32 v194, 0x45800000, v192
	v_cndmask_b32_e64 v194, v192, v194, s[2:3]
	v_mul_f32_e32 v192, 0x4b800000, v200
	v_cndmask_b32_e32 v192, v200, v192, vcc
	v_mov_b32_e32 v200, v149
	v_mov_b32_e32 v149, v151
	v_pk_add_f32 v[148:149], v[200:201], v[148:149]
	v_mov_b32_e32 v200, v145
	v_mov_b32_e32 v201, v146
	v_mov_b32_e32 v145, v147
	v_pk_add_f32 v[144:145], v[200:201], v[144:145]
	v_pk_add_f32 v[148:149], v[148:149], v[148:149] op_sel:[0,1] op_sel_hi:[1,0]
	v_pk_add_f32 v[144:145], v[144:145], v[144:145] op_sel:[0,1] op_sel_hi:[1,0]
	v_mov_b32_e32 v149, v148
	v_mov_b32_e32 v145, v144
	s_nop 0
	v_permlane16_swap_b32_e32 v148, v149
	v_permlane16_swap_b32_e32 v144, v145
	v_add_f32_e32 v149, v148, v149
	v_add_f32_e32 v148, v144, v145
	v_mov_b32_e32 v151, v149
	v_mov_b32_e32 v150, v148
	s_nop 0
	v_permlane32_swap_b32_e32 v149, v151
	v_permlane32_swap_b32_e32 v148, v150
	v_pk_add_f32 v[144:145], v[148:149], v[150:151]
	v_mov_b32_e32 v148, v141
	v_mov_b32_e32 v149, v142
	v_mov_b32_e32 v141, v143
	v_pk_add_f32 v[140:141], v[148:149], v[140:141]
	v_mov_b32_e32 v148, v137
	v_mov_b32_e32 v149, v138
	v_mov_b32_e32 v137, v139
	v_pk_add_f32 v[136:137], v[148:149], v[136:137]
	v_pk_add_f32 v[140:141], v[140:141], v[140:141] op_sel:[0,1] op_sel_hi:[1,0]
	v_pk_add_f32 v[136:137], v[136:137], v[136:137] op_sel:[0,1] op_sel_hi:[1,0]
	v_mov_b32_e32 v141, v140
	v_mov_b32_e32 v137, v136
	v_pk_fma_f32 v[144:145], v[144:145], s[44:45], v[196:197] op_sel_hi:[1,0,0]
	v_permlane16_swap_b32_e32 v140, v141
	v_permlane16_swap_b32_e32 v136, v137
	v_mul_f32_e32 v146, 0x4b800000, v145
	v_cmp_gt_f32_e64 s[2:3], s89, v145
	v_add_f32_e32 v141, v140, v141
	v_add_f32_e32 v140, v136, v137
	v_cndmask_b32_e64 v145, v145, v146, s[2:3]
	v_mov_b32_e32 v143, v141
	v_mov_b32_e32 v142, v140
	v_rsq_f32_e32 v192, v192
	v_rsq_f32_e32 v145, v145
	v_permlane32_swap_b32_e32 v141, v143
	v_permlane32_swap_b32_e32 v140, v142
	v_pk_add_f32 v[136:137], v[140:141], v[142:143]
	v_mov_b32_e32 v140, v133
	v_mov_b32_e32 v141, v134
	v_mov_b32_e32 v133, v135
	v_pk_add_f32 v[132:133], v[140:141], v[132:133]
	v_mov_b32_e32 v140, v129
	v_mov_b32_e32 v141, v130
	v_mov_b32_e32 v129, v131
	v_pk_add_f32 v[128:129], v[140:141], v[128:129]
	v_mul_f32_e32 v199, 0x45800000, v192
	v_mul_f32_e32 v146, 0x45800000, v145
	v_pk_fma_f32 v[136:137], v[136:137], s[44:45], v[196:197] op_sel_hi:[1,0,0]
	v_pk_add_f32 v[132:133], v[132:133], v[132:133] op_sel:[0,1] op_sel_hi:[1,0]
	v_pk_add_f32 v[128:129], v[128:129], v[128:129] op_sel:[0,1] op_sel_hi:[1,0]
	v_cndmask_b32_e32 v192, v192, v199, vcc
	v_cmp_gt_f32_e32 vcc, s89, v144
	v_cndmask_b32_e64 v146, v145, v146, s[2:3]
	v_mul_f32_e32 v145, 0x4b800000, v144
	v_mul_f32_e32 v138, 0x4b800000, v137
; __device__ __forceinline__ void gst16nt(void* p, u32x4 v) { __builtin_nontemporal_store(v, (g_u32x4*)p); }
; __device__ __forceinline__ u32x4 pack8(f32x4 v0, f32x4 v1) { u32x4 w; w.x = cvt_pk_bf16(v0[0], v0[1]); w.y = cvt_pk_bf16(v0[2], v0[3]); w.z = cvt_pk_bf16(v1[0], v1[1]); w.w = cvt_pk_bf16(v1[2], v1[3]); return w; }
;     __device__ __forceinline__ void operator()(EPI_ARGS) const {
;     ...
;               for (int m = 0; m < 4; ++m) rs[ai][m] = rsqrtf(red4((pa[ai][m][0] + pa[ai][m][1]) + (pa[ai][m][2] + pa[ai][m][3])) * (1.0f / 1024.0f) + EPS); }
; #pragma unroll
;         for (int ai = 0; ai < 2; ++ai)
; #pragma unroll
;             for (int m = 0; m < 4; ++m) { const int row = row0 + ai * HALF + m * 16; const float r = rs[ai][m];
; #pragma unroll
;                 for (int bj = 0; bj < 2; ++bj) { f32x4 v0 = acc[ai][bj][m][0] * r, v1 = acc[ai][bj][m][1] * r;
;                     if (ACT == 1) {
; #pragma unroll
;                         for (int j = 0; j < 4; ++j) { const float x = fmaxf(v0[j], 0.f), y = fmaxf(v1[j], 0.f); v0[j] = x * x; v1[j] = y * y; } }
;                     const int c = col0 + bj * HALF;
;                     if (UMODE == 0) { if (ACT == 1) gst16nt(O + (size_t)row * ldc + c, pack8(v0, v1)); else gst16(O + (size_t)row * ldc + c, pack8(v0, v1)); }
	v_cmp_gt_f32_e64 s[2:3], s89, v137
	v_mov_b32_e32 v133, v132
	v_mov_b32_e32 v129, v128
	v_cndmask_b32_e32 v144, v144, v145, vcc
	v_cndmask_b32_e64 v137, v137, v138, s[2:3]
	v_permlane16_swap_b32_e32 v132, v133
	v_permlane16_swap_b32_e32 v128, v129
	v_rsq_f32_e32 v144, v144
	v_rsq_f32_e32 v137, v137
	v_add_f32_e32 v133, v132, v133
	v_add_f32_e32 v132, v128, v129
	v_mov_b32_e32 v135, v133
	v_mov_b32_e32 v134, v132
	s_nop 0
	v_permlane32_swap_b32_e32 v133, v135
	v_permlane32_swap_b32_e32 v132, v134
	v_pk_add_f32 v[128:129], v[132:133], v[134:135]
	v_mul_f32_e32 v145, 0x45800000, v144
	v_mul_f32_e32 v138, 0x45800000, v137
	v_pk_fma_f32 v[128:129], v[128:129], s[44:45], v[196:197] op_sel_hi:[1,0,0]
	v_cndmask_b32_e32 v144, v144, v145, vcc
	v_cmp_gt_f32_e32 vcc, s89, v136
	v_cndmask_b32_e64 v138, v137, v138, s[2:3]
	v_mul_f32_e32 v137, 0x4b800000, v136
	v_mul_f32_e32 v130, 0x4b800000, v129
	v_cmp_gt_f32_e64 s[2:3], s89, v129
	v_cndmask_b32_e32 v136, v136, v137, vcc
	v_rsq_f32_e32 v136, v136
	v_cndmask_b32_e64 v129, v129, v130, s[2:3]
	v_rsq_f32_e32 v129, v129
	v_pk_mul_f32 v[120:121], v[120:121], v[194:195] op_sel_hi:[1,0]
	v_mul_f32_e32 v137, 0x45800000, v136
	v_cndmask_b32_e32 v136, v136, v137, vcc
	v_mul_f32_e32 v130, 0x45800000, v129
	v_cmp_gt_f32_e32 vcc, s89, v128
	v_cndmask_b32_e64 v130, v129, v130, s[2:3]
	v_mul_f32_e32 v129, 0x4b800000, v128
	v_cndmask_b32_e32 v128, v128, v129, vcc
	v_rsq_f32_e32 v128, v128
	v_pk_mul_f32 v[124:125], v[124:125], v[194:195] op_sel_hi:[1,0]
	v_max_f32_e32 v120, 0, v120
	v_pk_mul_f32 v[126:127], v[126:127], v[194:195] op_sel_hi:[1,0]
	v_mul_f32_e32 v129, 0x45800000, v128
	v_cndmask_b32_e32 v128, v128, v129, vcc
	v_pk_mul_f32 v[122:123], v[122:123], v[194:195] op_sel_hi:[1,0]
	v_mul_f32_e32 v129, v120, v120
	v_max_f32_e32 v120, 0, v125
	v_max_f32_e32 v121, 0, v121
	v_mul_f32_e32 v125, v120, v120
	v_mul_f32_e32 v131, v121, v121
	v_max_f32_e32 v120, 0, v126
	v_max_f32_e32 v121, 0, v122
	v_lshl_or_b32 v132, s51, 8, v195
	v_mul_f32_e32 v134, v120, v120
	v_mul_f32_e32 v135, v121, v121
	v_max_f32_e32 v120, 0, v127
	v_max_f32_e32 v121, 0, v123
	v_mul_f32_e32 v137, v120, v120
	v_mul_f32_e32 v139, v121, v121
	v_lshlrev_b64 v[120:121], 13, v[190:191]
	v_ashrrev_i32_e32 v133, 31, v132
	v_max_f32_e32 v124, 0, v124
	v_lshl_add_u64 v[122:123], s[24:25], 0, v[120:121]
	v_lshlrev_b64 v[120:121], 1, v[132:133]
	v_pk_mul_f32 v[112:113], v[112:113], v[194:195] op_sel_hi:[1,0]
	v_mul_f32_e32 v124, v124, v124
	v_lshl_add_u64 v[126:127], v[122:123], 0, v[120:121]
	v_cvt_pk_bf16_f32 v122, v124, v125
	v_pk_mul_f32 v[118:119], v[118:119], v[194:195] op_sel_hi:[1,0]
	v_pk_mul_f32 v[116:117], v[116:117], v[194:195] op_sel_hi:[1,0]
	v_pk_mul_f32 v[114:115], v[114:115], v[194:195] op_sel_hi:[1,0]
	v_max_f32_e32 v112, 0, v112
	v_max_f32_e32 v113, 0, v113
	v_cvt_pk_bf16_f32 v123, v134, v137
	v_cvt_pk_bf16_f32 v124, v129, v131
	v_cvt_pk_bf16_f32 v125, v135, v139
	global_store_dwordx4 v[126:127], v[122:125], off nt
	v_max_f32_e32 v114, 0, v114
	v_max_f32_e32 v116, 0, v116
	v_mul_f32_e32 v122, v112, v112
	v_max_f32_e32 v112, 0, v117
	v_mul_f32_e32 v117, v113, v113
	v_max_f32_e32 v113, 0, v118
	v_mul_f32_e32 v112, v112, v112
	v_mul_f32_e32 v113, v113, v113
	v_mul_f32_e32 v118, v114, v114
	v_max_f32_e32 v114, 0, v119
	v_max_f32_e32 v115, 0, v115
	v_pk_mul_f32 v[104:105], v[104:105], v[192:193] op_sel_hi:[1,0]
	v_mul_f32_e32 v116, v116, v116
	v_mul_f32_e32 v114, v114, v114
	v_mul_f32_e32 v115, v115, v115
	v_cvt_pk_bf16_f32 v112, v116, v112
	v_cvt_pk_bf16_f32 v113, v113, v114
	v_pk_mul_f32 v[108:109], v[108:109], v[192:193] op_sel_hi:[1,0]
	v_max_f32_e32 v104, 0, v104
	v_cvt_pk_bf16_f32 v114, v122, v117
	v_cvt_pk_bf16_f32 v115, v118, v115
	global_store_dwordx4 v[126:127], v[112:115], off offset:256 nt
	v_pk_mul_f32 v[110:111], v[110:111], v[192:193] op_sel_hi:[1,0]
	v_pk_mul_f32 v[106:107], v[106:107], v[192:193] op_sel_hi:[1,0]
	v_mul_f32_e32 v113, v104, v104
	v_max_f32_e32 v104, 0, v109
	v_max_f32_e32 v105, 0, v105
	v_mul_f32_e32 v114, v104, v104
	v_mul_f32_e32 v115, v105, v105
	v_max_f32_e32 v104, 0, v110
	v_max_f32_e32 v105, 0, v106
	v_mul_f32_e32 v106, v104, v104
	v_mul_f32_e32 v110, v105, v105
	v_max_f32_e32 v104, 0, v111
	v_max_f32_e32 v105, 0, v107
	v_mul_f32_e32 v107, v104, v104
	v_mul_f32_e32 v111, v105, v105
	v_lshlrev_b64 v[104:105], 13, v[188:189]
	v_max_f32_e32 v108, 0, v108
	v_lshl_add_u64 v[104:105], s[24:25], 0, v[104:105]
	v_pk_mul_f32 v[96:97], v[96:97], v[192:193] op_sel_hi:[1,0]
	v_mul_f32_e32 v112, v108, v108
	v_lshl_add_u64 v[108:109], v[104:105], 0, v[120:121]
	v_cvt_pk_bf16_f32 v104, v112, v114
	v_pk_mul_f32 v[102:103], v[102:103], v[192:193] op_sel_hi:[1,0]
	v_pk_mul_f32 v[100:101], v[100:101], v[192:193] op_sel_hi:[1,0]
	v_pk_mul_f32 v[98:99], v[98:99], v[192:193] op_sel_hi:[1,0]
	v_max_f32_e32 v96, 0, v96
	v_max_f32_e32 v97, 0, v97
	v_cvt_pk_bf16_f32 v105, v106, v107
	v_cvt_pk_bf16_f32 v106, v113, v115
	v_cvt_pk_bf16_f32 v107, v110, v111
	global_store_dwordx4 v[108:109], v[104:107], off nt
	v_max_f32_e32 v98, 0, v98
	v_max_f32_e32 v100, 0, v100
	v_mul_f32_e32 v104, v96, v96
	v_max_f32_e32 v96, 0, v101
	v_mul_f32_e32 v101, v97, v97
	v_max_f32_e32 v97, 0, v102
	v_mul_f32_e32 v96, v96, v96
	v_mul_f32_e32 v97, v97, v97
	v_mul_f32_e32 v102, v98, v98
	v_max_f32_e32 v98, 0, v103
	v_max_f32_e32 v99, 0, v99
	v_pk_mul_f32 v[88:89], v[88:89], v[146:147] op_sel_hi:[1,0]
	v_mul_f32_e32 v100, v100, v100
	v_mul_f32_e32 v98, v98, v98
	v_mul_f32_e32 v99, v99, v99
	v_cvt_pk_bf16_f32 v96, v100, v96
	v_cvt_pk_bf16_f32 v97, v97, v98
	v_pk_mul_f32 v[92:93], v[92:93], v[146:147] op_sel_hi:[1,0]
	v_max_f32_e32 v88, 0, v88
; __device__ __forceinline__ void gst16nt(void* p, u32x4 v) { __builtin_nontemporal_store(v, (g_u32x4*)p); }
; __device__ __forceinline__ u32x4 pack8(f32x4 v0, f32x4 v1) { u32x4 w; w.x = cvt_pk_bf16(v0[0], v0[1]); w.y = cvt_pk_bf16(v0[2], v0[3]); w.z = cvt_pk_bf16(v1[0], v1[1]); w.w = cvt_pk_bf16(v1[2], v1[3]); return w; }
;     __device__ __forceinline__ void operator()(EPI_ARGS) const {
;     ...
;         for (int ai = 0; ai < 2; ++ai)
; #pragma unroll
;             for (int m = 0; m < 4; ++m) { const int row = row0 + ai * HALF + m * 16; const float r = rs[ai][m];
; #pragma unroll
;                 for (int bj = 0; bj < 2; ++bj) { f32x4 v0 = acc[ai][bj][m][0] * r, v1 = acc[ai][bj][m][1] * r;
;                     if (ACT == 1) {
; #pragma unroll
;                         for (int j = 0; j < 4; ++j) { const float x = fmaxf(v0[j], 0.f), y = fmaxf(v1[j], 0.f); v0[j] = x * x; v1[j] = y * y; } }
;                     const int c = col0 + bj * HALF;
;                     if (UMODE == 0) { if (ACT == 1) gst16nt(O + (size_t)row * ldc + c, pack8(v0, v1)); else gst16(O + (size_t)row * ldc + c, pack8(v0, v1)); }
	v_cvt_pk_bf16_f32 v98, v104, v101
	v_cvt_pk_bf16_f32 v99, v102, v99
	global_store_dwordx4 v[108:109], v[96:99], off offset:256 nt
	v_pk_mul_f32 v[94:95], v[94:95], v[146:147] op_sel_hi:[1,0]
	v_pk_mul_f32 v[90:91], v[90:91], v[146:147] op_sel_hi:[1,0]
	v_mul_f32_e32 v97, v88, v88
	v_max_f32_e32 v88, 0, v93
	v_max_f32_e32 v89, 0, v89
	v_mul_f32_e32 v98, v88, v88
	v_mul_f32_e32 v99, v89, v89
	v_max_f32_e32 v88, 0, v94
	v_max_f32_e32 v89, 0, v90
	v_mul_f32_e32 v90, v88, v88
	v_mul_f32_e32 v94, v89, v89
	v_max_f32_e32 v88, 0, v95
	v_max_f32_e32 v89, 0, v91
	v_mul_f32_e32 v91, v88, v88
	v_mul_f32_e32 v95, v89, v89
	v_lshlrev_b64 v[88:89], 13, v[186:187]
	v_max_f32_e32 v92, 0, v92
	v_lshl_add_u64 v[88:89], s[24:25], 0, v[88:89]
	v_pk_mul_f32 v[80:81], v[80:81], v[146:147] op_sel_hi:[1,0]
	v_mul_f32_e32 v96, v92, v92
	v_lshl_add_u64 v[92:93], v[88:89], 0, v[120:121]
	v_cvt_pk_bf16_f32 v88, v96, v98
	v_pk_mul_f32 v[86:87], v[86:87], v[146:147] op_sel_hi:[1,0]
	v_pk_mul_f32 v[84:85], v[84:85], v[146:147] op_sel_hi:[1,0]
	v_pk_mul_f32 v[82:83], v[82:83], v[146:147] op_sel_hi:[1,0]
	v_max_f32_e32 v80, 0, v80
	v_max_f32_e32 v81, 0, v81
	v_cvt_pk_bf16_f32 v89, v90, v91
	v_cvt_pk_bf16_f32 v90, v97, v99
	v_cvt_pk_bf16_f32 v91, v94, v95
	global_store_dwordx4 v[92:93], v[88:91], off nt
	v_max_f32_e32 v82, 0, v82
	v_max_f32_e32 v84, 0, v84
	v_mul_f32_e32 v88, v80, v80
	v_max_f32_e32 v80, 0, v85
	v_mul_f32_e32 v85, v81, v81
	v_max_f32_e32 v81, 0, v86
	v_mul_f32_e32 v80, v80, v80
	v_mul_f32_e32 v81, v81, v81
	v_mul_f32_e32 v86, v82, v82
	v_max_f32_e32 v82, 0, v87
	v_max_f32_e32 v83, 0, v83
	v_pk_mul_f32 v[72:73], v[72:73], v[144:145] op_sel_hi:[1,0]
	v_mul_f32_e32 v84, v84, v84
	v_mul_f32_e32 v82, v82, v82
	v_mul_f32_e32 v83, v83, v83
	v_cvt_pk_bf16_f32 v80, v84, v80
	v_cvt_pk_bf16_f32 v81, v81, v82
	v_pk_mul_f32 v[76:77], v[76:77], v[144:145] op_sel_hi:[1,0]
	v_max_f32_e32 v72, 0, v72
	v_cvt_pk_bf16_f32 v82, v88, v85
	v_cvt_pk_bf16_f32 v83, v86, v83
	global_store_dwordx4 v[92:93], v[80:83], off offset:256 nt
	v_pk_mul_f32 v[78:79], v[78:79], v[144:145] op_sel_hi:[1,0]
	v_pk_mul_f32 v[74:75], v[74:75], v[144:145] op_sel_hi:[1,0]
	v_mul_f32_e32 v81, v72, v72
	v_max_f32_e32 v72, 0, v77
	v_max_f32_e32 v73, 0, v73
	v_mul_f32_e32 v82, v72, v72
	v_mul_f32_e32 v83, v73, v73
	v_max_f32_e32 v72, 0, v78
	v_max_f32_e32 v73, 0, v74
	v_mul_f32_e32 v74, v72, v72
	v_mul_f32_e32 v78, v73, v73
	v_max_f32_e32 v72, 0, v79
	v_max_f32_e32 v73, 0, v75
	v_mul_f32_e32 v75, v72, v72
	v_mul_f32_e32 v79, v73, v73
	v_lshlrev_b64 v[72:73], 13, v[184:185]
	v_max_f32_e32 v76, 0, v76
	v_lshl_add_u64 v[72:73], s[24:25], 0, v[72:73]
	v_pk_mul_f32 v[64:65], v[64:65], v[144:145] op_sel_hi:[1,0]
	v_mul_f32_e32 v80, v76, v76
	v_lshl_add_u64 v[76:77], v[72:73], 0, v[120:121]
	v_cvt_pk_bf16_f32 v72, v80, v82
	v_pk_mul_f32 v[70:71], v[70:71], v[144:145] op_sel_hi:[1,0]
	v_pk_mul_f32 v[68:69], v[68:69], v[144:145] op_sel_hi:[1,0]
	v_pk_mul_f32 v[66:67], v[66:67], v[144:145] op_sel_hi:[1,0]
	v_max_f32_e32 v64, 0, v64
	v_max_f32_e32 v65, 0, v65
	v_cvt_pk_bf16_f32 v73, v74, v75
	v_cvt_pk_bf16_f32 v74, v81, v83
	v_cvt_pk_bf16_f32 v75, v78, v79
	global_store_dwordx4 v[76:77], v[72:75], off nt
	v_max_f32_e32 v66, 0, v66
	v_max_f32_e32 v68, 0, v68
	v_mul_f32_e32 v72, v64, v64
	v_max_f32_e32 v64, 0, v69
	v_mul_f32_e32 v69, v65, v65
	v_max_f32_e32 v65, 0, v70
	v_mul_f32_e32 v64, v64, v64
	v_mul_f32_e32 v65, v65, v65
	v_mul_f32_e32 v70, v66, v66
	v_max_f32_e32 v66, 0, v71
	v_max_f32_e32 v67, 0, v67
	v_pk_mul_f32 v[56:57], v[56:57], v[138:139] op_sel_hi:[1,0]
	v_mul_f32_e32 v68, v68, v68
	v_mul_f32_e32 v66, v66, v66
	v_mul_f32_e32 v67, v67, v67
	v_cvt_pk_bf16_f32 v64, v68, v64
	v_cvt_pk_bf16_f32 v65, v65, v66
	v_pk_mul_f32 v[60:61], v[60:61], v[138:139] op_sel_hi:[1,0]
	v_max_f32_e32 v56, 0, v56
	v_cvt_pk_bf16_f32 v66, v72, v69
	v_cvt_pk_bf16_f32 v67, v70, v67
	global_store_dwordx4 v[76:77], v[64:67], off offset:256 nt
	v_pk_mul_f32 v[62:63], v[62:63], v[138:139] op_sel_hi:[1,0]
	v_pk_mul_f32 v[58:59], v[58:59], v[138:139] op_sel_hi:[1,0]
	v_mul_f32_e32 v65, v56, v56
	v_max_f32_e32 v56, 0, v61
	v_max_f32_e32 v57, 0, v57
	v_mul_f32_e32 v66, v56, v56
	v_mul_f32_e32 v67, v57, v57
	v_max_f32_e32 v56, 0, v62
	v_max_f32_e32 v57, 0, v58
	v_mul_f32_e32 v58, v56, v56
	v_mul_f32_e32 v62, v57, v57
	v_max_f32_e32 v56, 0, v63
	v_max_f32_e32 v57, 0, v59
	v_mul_f32_e32 v59, v56, v56
	v_mul_f32_e32 v63, v57, v57
	v_lshlrev_b64 v[56:57], 13, v[182:183]
	v_max_f32_e32 v60, 0, v60
	v_lshl_add_u64 v[56:57], s[24:25], 0, v[56:57]
	v_pk_mul_f32 v[48:49], v[48:49], v[138:139] op_sel_hi:[1,0]
	v_mul_f32_e32 v64, v60, v60
	v_lshl_add_u64 v[60:61], v[56:57], 0, v[120:121]
	v_cvt_pk_bf16_f32 v56, v64, v66
	v_pk_mul_f32 v[54:55], v[54:55], v[138:139] op_sel_hi:[1,0]
	v_pk_mul_f32 v[52:53], v[52:53], v[138:139] op_sel_hi:[1,0]
	v_pk_mul_f32 v[50:51], v[50:51], v[138:139] op_sel_hi:[1,0]
	v_max_f32_e32 v48, 0, v48
	v_max_f32_e32 v49, 0, v49
	v_cvt_pk_bf16_f32 v57, v58, v59
	v_cvt_pk_bf16_f32 v58, v65, v67
	v_cvt_pk_bf16_f32 v59, v62, v63
	global_store_dwordx4 v[60:61], v[56:59], off nt
	v_max_f32_e32 v50, 0, v50
	v_max_f32_e32 v52, 0, v52
	v_mul_f32_e32 v56, v48, v48
	v_max_f32_e32 v48, 0, v53
	v_mul_f32_e32 v53, v49, v49
	v_max_f32_e32 v49, 0, v54
	v_mul_f32_e32 v48, v48, v48
	v_mul_f32_e32 v49, v49, v49
	v_mul_f32_e32 v54, v50, v50
	v_max_f32_e32 v50, 0, v55
	v_max_f32_e32 v51, 0, v51
	v_pk_mul_f32 v[40:41], v[40:41], v[136:137] op_sel_hi:[1,0]
	v_mul_f32_e32 v52, v52, v52
	v_mul_f32_e32 v50, v50, v50
	v_mul_f32_e32 v51, v51, v51
	v_cvt_pk_bf16_f32 v48, v52, v48
	v_cvt_pk_bf16_f32 v49, v49, v50
	v_pk_mul_f32 v[44:45], v[44:45], v[136:137] op_sel_hi:[1,0]
; __device__ __forceinline__ void gst16nt(void* p, u32x4 v) { __builtin_nontemporal_store(v, (g_u32x4*)p); }
; __device__ __forceinline__ u32x4 pack8(f32x4 v0, f32x4 v1) { u32x4 w; w.x = cvt_pk_bf16(v0[0], v0[1]); w.y = cvt_pk_bf16(v0[2], v0[3]); w.z = cvt_pk_bf16(v1[0], v1[1]); w.w = cvt_pk_bf16(v1[2], v1[3]); return w; }
; #define PG8_BAR __builtin_amdgcn_s_barrier()
;     __device__ __forceinline__ void operator()(EPI_ARGS) const {
;     ...
;         for (int ai = 0; ai < 2; ++ai)
; #pragma unroll
;             for (int m = 0; m < 4; ++m) { const int row = row0 + ai * HALF + m * 16; const float r = rs[ai][m];
; #pragma unroll
;                 for (int bj = 0; bj < 2; ++bj) { f32x4 v0 = acc[ai][bj][m][0] * r, v1 = acc[ai][bj][m][1] * r;
;                     if (ACT == 1) {
; #pragma unroll
;                         for (int j = 0; j < 4; ++j) { const float x = fmaxf(v0[j], 0.f), y = fmaxf(v1[j], 0.f); v0[j] = x * x; v1[j] = y * y; } }
;                     const int c = col0 + bj * HALF;
;                     if (UMODE == 0) { if (ACT == 1) gst16nt(O + (size_t)row * ldc + c, pack8(v0, v1)); else gst16(O + (size_t)row * ldc + c, pack8(v0, v1)); }
;     ...
;         if (!has_next) break;
; #pragma unroll
;         for (int a = 0; a < 2; ++a)
; #pragma unroll
;             for (int b = 0; b < 2; ++b)
; #pragma unroll
;                 for (int m = 0; m < 4; ++m)
; #pragma unroll
;                     for (int n = 0; n < 2; ++n) acc[a][b][m][n] = (f32x4){0.f, 0.f, 0.f, 0.f};
;         cur = nxt; cA = nA; cA2 = nA2; cB = nB; ++ui;
;         if constexpr (ALIGN_EPI) { if (wr == 1) PG8_BAR; }
	v_max_f32_e32 v40, 0, v40
	v_cvt_pk_bf16_f32 v50, v56, v53
	v_cvt_pk_bf16_f32 v51, v54, v51
	global_store_dwordx4 v[60:61], v[48:51], off offset:256 nt
	v_pk_mul_f32 v[46:47], v[46:47], v[136:137] op_sel_hi:[1,0]
	v_pk_mul_f32 v[42:43], v[42:43], v[136:137] op_sel_hi:[1,0]
	v_mul_f32_e32 v49, v40, v40
	v_max_f32_e32 v40, 0, v45
	v_max_f32_e32 v41, 0, v41
	v_mul_f32_e32 v50, v40, v40
	v_mul_f32_e32 v51, v41, v41
	v_max_f32_e32 v40, 0, v46
	v_max_f32_e32 v41, 0, v42
	v_mul_f32_e32 v42, v40, v40
	v_mul_f32_e32 v46, v41, v41
	v_max_f32_e32 v40, 0, v47
	v_max_f32_e32 v41, 0, v43
	v_mul_f32_e32 v43, v40, v40
	v_mul_f32_e32 v47, v41, v41
	v_lshlrev_b64 v[40:41], 13, v[180:181]
	v_max_f32_e32 v44, 0, v44
	v_lshl_add_u64 v[40:41], s[24:25], 0, v[40:41]
	v_pk_mul_f32 v[32:33], v[32:33], v[136:137] op_sel_hi:[1,0]
	v_mul_f32_e32 v48, v44, v44
	v_lshl_add_u64 v[44:45], v[40:41], 0, v[120:121]
	v_cvt_pk_bf16_f32 v40, v48, v50
	v_pk_mul_f32 v[38:39], v[38:39], v[136:137] op_sel_hi:[1,0]
	v_pk_mul_f32 v[36:37], v[36:37], v[136:137] op_sel_hi:[1,0]
	v_pk_mul_f32 v[34:35], v[34:35], v[136:137] op_sel_hi:[1,0]
	v_max_f32_e32 v32, 0, v32
	v_max_f32_e32 v33, 0, v33
	v_cvt_pk_bf16_f32 v41, v42, v43
	v_cvt_pk_bf16_f32 v42, v49, v51
	v_cvt_pk_bf16_f32 v43, v46, v47
	global_store_dwordx4 v[44:45], v[40:43], off nt
	v_max_f32_e32 v34, 0, v34
	v_max_f32_e32 v36, 0, v36
	v_mul_f32_e32 v40, v32, v32
	v_max_f32_e32 v32, 0, v37
	v_mul_f32_e32 v37, v33, v33
	v_max_f32_e32 v33, 0, v38
	v_mul_f32_e32 v32, v32, v32
	v_mul_f32_e32 v33, v33, v33
	v_mul_f32_e32 v38, v34, v34
	v_max_f32_e32 v34, 0, v39
	v_max_f32_e32 v35, 0, v35
	v_pk_mul_f32 v[24:25], v[24:25], v[130:131] op_sel_hi:[1,0]
	v_mul_f32_e32 v36, v36, v36
	v_mul_f32_e32 v34, v34, v34
	v_mul_f32_e32 v35, v35, v35
	v_cvt_pk_bf16_f32 v32, v36, v32
	v_cvt_pk_bf16_f32 v33, v33, v34
	v_pk_mul_f32 v[28:29], v[28:29], v[130:131] op_sel_hi:[1,0]
	v_max_f32_e32 v24, 0, v24
	v_cvt_pk_bf16_f32 v34, v40, v37
	v_cvt_pk_bf16_f32 v35, v38, v35
	global_store_dwordx4 v[44:45], v[32:35], off offset:256 nt
	v_pk_mul_f32 v[30:31], v[30:31], v[130:131] op_sel_hi:[1,0]
	v_pk_mul_f32 v[26:27], v[26:27], v[130:131] op_sel_hi:[1,0]
	v_mul_f32_e32 v33, v24, v24
	v_max_f32_e32 v24, 0, v29
	v_max_f32_e32 v25, 0, v25
	v_mul_f32_e32 v34, v24, v24
	v_mul_f32_e32 v35, v25, v25
	v_max_f32_e32 v24, 0, v30
	v_max_f32_e32 v25, 0, v26
	v_mul_f32_e32 v26, v24, v24
	v_mul_f32_e32 v30, v25, v25
	v_max_f32_e32 v24, 0, v31
	v_max_f32_e32 v25, 0, v27
	v_mul_f32_e32 v27, v24, v24
	v_mul_f32_e32 v31, v25, v25
	v_lshlrev_b64 v[24:25], 13, v[178:179]
	v_max_f32_e32 v28, 0, v28
	v_lshl_add_u64 v[24:25], s[24:25], 0, v[24:25]
	v_pk_mul_f32 v[16:17], v[16:17], v[130:131] op_sel_hi:[1,0]
	v_mul_f32_e32 v32, v28, v28
	v_lshl_add_u64 v[28:29], v[24:25], 0, v[120:121]
	v_cvt_pk_bf16_f32 v24, v32, v34
	v_pk_mul_f32 v[22:23], v[22:23], v[130:131] op_sel_hi:[1,0]
	v_pk_mul_f32 v[20:21], v[20:21], v[130:131] op_sel_hi:[1,0]
	v_pk_mul_f32 v[18:19], v[18:19], v[130:131] op_sel_hi:[1,0]
	v_max_f32_e32 v16, 0, v16
	v_max_f32_e32 v17, 0, v17
	v_cvt_pk_bf16_f32 v25, v26, v27
	v_cvt_pk_bf16_f32 v26, v33, v35
	v_cvt_pk_bf16_f32 v27, v30, v31
	global_store_dwordx4 v[28:29], v[24:27], off nt
	v_max_f32_e32 v18, 0, v18
	v_max_f32_e32 v20, 0, v20
	v_mul_f32_e32 v24, v16, v16
	v_max_f32_e32 v16, 0, v21
	v_mul_f32_e32 v21, v17, v17
	v_max_f32_e32 v17, 0, v22
	v_mul_f32_e32 v16, v16, v16
	v_mul_f32_e32 v17, v17, v17
	v_mul_f32_e32 v22, v18, v18
	v_max_f32_e32 v18, 0, v23
	v_max_f32_e32 v19, 0, v19
	v_pk_mul_f32 v[8:9], v[8:9], v[128:129] op_sel_hi:[1,0]
	v_mul_f32_e32 v20, v20, v20
	v_mul_f32_e32 v18, v18, v18
	v_mul_f32_e32 v19, v19, v19
	v_cvt_pk_bf16_f32 v16, v20, v16
	v_cvt_pk_bf16_f32 v17, v17, v18
	v_pk_mul_f32 v[12:13], v[12:13], v[128:129] op_sel_hi:[1,0]
	v_max_f32_e32 v8, 0, v8
	v_cvt_pk_bf16_f32 v18, v24, v21
	v_cvt_pk_bf16_f32 v19, v22, v19
	global_store_dwordx4 v[28:29], v[16:19], off offset:256 nt
	v_pk_mul_f32 v[14:15], v[14:15], v[128:129] op_sel_hi:[1,0]
	v_pk_mul_f32 v[10:11], v[10:11], v[128:129] op_sel_hi:[1,0]
	v_mul_f32_e32 v17, v8, v8
	v_max_f32_e32 v8, 0, v13
	v_max_f32_e32 v9, 0, v9
	v_mul_f32_e32 v18, v8, v8
	v_mul_f32_e32 v19, v9, v9
	v_max_f32_e32 v8, 0, v14
	v_max_f32_e32 v9, 0, v10
	v_mul_f32_e32 v10, v8, v8
	v_mul_f32_e32 v14, v9, v9
	v_max_f32_e32 v8, 0, v15
	v_max_f32_e32 v9, 0, v11
	v_mul_f32_e32 v11, v8, v8
	v_mul_f32_e32 v15, v9, v9
	v_lshlrev_b64 v[8:9], 13, v[176:177]
	v_max_f32_e32 v12, 0, v12
	v_lshl_add_u64 v[8:9], s[24:25], 0, v[8:9]
	v_pk_mul_f32 v[2:3], v[2:3], v[128:129] op_sel_hi:[1,0]
	v_pk_mul_f32 v[0:1], v[0:1], v[128:129] op_sel_hi:[1,0]
	v_mul_f32_e32 v16, v12, v12
	v_lshl_add_u64 v[12:13], v[8:9], 0, v[120:121]
	v_cvt_pk_bf16_f32 v8, v16, v18
	v_pk_mul_f32 v[6:7], v[6:7], v[128:129] op_sel_hi:[1,0]
	v_pk_mul_f32 v[4:5], v[4:5], v[128:129] op_sel_hi:[1,0]
	v_max_f32_e32 v0, 0, v0
	v_max_f32_e32 v1, 0, v1
	v_max_f32_e32 v2, 0, v2
	v_cvt_pk_bf16_f32 v9, v10, v11
	v_cvt_pk_bf16_f32 v10, v17, v19
	v_cvt_pk_bf16_f32 v11, v14, v15
	global_store_dwordx4 v[12:13], v[8:11], off nt
	v_max_f32_e32 v3, 0, v3
	v_max_f32_e32 v4, 0, v4
	v_mul_f32_e32 v8, v0, v0
	v_max_f32_e32 v0, 0, v5
	v_mul_f32_e32 v5, v1, v1
	v_max_f32_e32 v1, 0, v6
	v_mul_f32_e32 v6, v2, v2
	v_max_f32_e32 v2, 0, v7
	v_mul_f32_e32 v0, v0, v0
	v_mul_f32_e32 v1, v1, v1
	v_mul_f32_e32 v2, v2, v2
	v_mul_f32_e32 v3, v3, v3
	s_mov_b64 s[2:3], -1
	s_andn2_b64 vcc, exec, s[40:41]
	v_mul_f32_e32 v4, v4, v4
	v_cvt_pk_bf16_f32 v0, v4, v0
	v_cvt_pk_bf16_f32 v1, v1, v2
	v_cvt_pk_bf16_f32 v2, v8, v5
	v_cvt_pk_bf16_f32 v3, v6, v3
	global_store_dwordx4 v[12:13], v[0:3], off offset:256 nt
	s_cbranch_vccnz .LBB0_291
	s_andn2_b64 vcc, exec, s[14:15]
	s_cbranch_vccnz .LBB0_290
	s_barrier
	s_branch .LBB0_290

; #define PG8_STAGE(bufoff, gbase, voff) do { _Pragma("unroll") for (int _i = 0; _i < 2; ++_i) \
;         __builtin_amdgcn_global_load_lds((const unsigned*)((const char*)(gbase) + (voff)[_i]), (LAS unsigned*)(lds + (bufoff) + ldsw + _i * 8192), 16, 0, 0); } while (0)
; #define PG8_LDA(dst, b, h) do { _Pragma("unroll") for (int m = 0; m < 4; ++m) _Pragma("unroll") for (int k = 0; k < 2; ++k) dst[m][k] = *(const LAS bf16x8*)(lds + PG8_SA(b, h) + aoff + m * 2048 + k * 1024); } while (0)
; #define PG8_LDB(dst, b, h) do { _Pragma("unroll") for (int n = 0; n < 2; ++n) _Pragma("unroll") for (int k = 0; k < 2; ++k) dst[n][k] = *(const LAS bf16x8*)(lds + PG8_SB(b, h) + boff + n * 2048 + k * 1024); } while (0)
; #define PG8_SCHED __builtin_amdgcn_sched_barrier(0)
;     ...
;         const bool has_next = S.next(ui + 1, nxt);
;         const char* nA = has_next ? oa.base + (size_t)nxt.pm * oa.tstep : cA; const char* nA2 = has_next ? oa.base2 + (size_t)nxt.pm * oa.tstep : cA2; const char* nB = has_next ? ob.base + (size_t)nxt.pn * ob.tstep : cB;
; #pragma nounroll
;         for (int t = 0; t < nt; t += 2) {
;             const bool last = (t == nt - 2);
;             const char* a1 = PG8_ATILE(cA, cA2, t + 1);
;             const char* a2 = last ? nA : PG8_ATILE(cA, cA2, t + 2); const char* b2 = last ? nB : cB + (size_t)(t + 2) * 128;
;             const char* a3 = last ? nA + kA1 : PG8_ATILE(cA, cA2, t + 3); const char* b3 = b2 + kB1;
;             if constexpr (SP2) {
;             PG8_LDB(B0, 0, 0); PG8_LDB(B1, 0, 1); PG8_SCHED; PG8_LDA(At, 0, 0); PG8_STAGE(PG8_SA(1, 1), a1 + hA, voffA);
;     ...
;         for (int a = 0; a < 2; ++a)
; #pragma unroll
;             for (int b = 0; b < 2; ++b)
; #pragma unroll
;                 for (int m = 0; m < 4; ++m)
; #pragma unroll
;                     for (int n = 0; n < 2; ++n) acc[a][b][m][n] = (f32x4){0.f, 0.f, 0.f, 0.f};
.LBB0_363:
	s_mov_b32 s42, s74
	s_mov_b32 s44, s43
	s_ashr_i32 s43, s74, 31
	s_lshl_b64 s[52:53], s[42:43], s80
	s_add_u32 s52, s78, s52
	s_addc_u32 s53, s89, s53
	s_mov_b32 s35, s73
	s_and_b64 s[72:73], s[90:91], exec
	s_mov_b32 s17, s45
	s_cselect_b32 s43, s53, s93
	s_cselect_b32 s82, s52, s92
	s_ashr_i32 s45, s44, 31
	s_lshl_b64 s[72:73], s[44:45], s80
	s_add_u32 s72, s12, s72
	s_addc_u32 s73, s13, s73
	s_and_b64 s[74:75], s[90:91], exec
	s_cselect_b32 s45, s73, s95
	s_cselect_b32 s96, s72, s94
	s_add_u32 s97, s82, 0x80
	s_addc_u32 s79, s43, 0
	s_add_u32 s94, s94, 0x100
	s_addc_u32 s95, s95, 0
	s_add_u32 s74, s92, 0x80
	s_addc_u32 s75, s93, 0
	v_mov_b32_e32 v0, 0
	v_lshl_add_u64 v[128:129], s[74:75], 0, v[142:143]
	v_lshl_add_u64 v[130:131], s[74:75], 0, v[144:145]
	s_mov_b32 s74, 0
	s_mov_b64 vcc, 0
	v_mov_b32_e32 v1, v0
	v_mov_b32_e32 v2, v0
	v_mov_b32_e32 v3, v0
	v_mov_b32_e32 v4, v0
	v_mov_b32_e32 v5, v0
	v_mov_b32_e32 v6, v0
	v_mov_b32_e32 v7, v0
	v_mov_b32_e32 v16, v0
	v_mov_b32_e32 v17, v0
	v_mov_b32_e32 v18, v0
	v_mov_b32_e32 v19, v0
	v_mov_b32_e32 v20, v0
	v_mov_b32_e32 v21, v0
	v_mov_b32_e32 v22, v0
	v_mov_b32_e32 v23, v0
	v_mov_b32_e32 v32, v0
	v_mov_b32_e32 v33, v0
	v_mov_b32_e32 v34, v0
	v_mov_b32_e32 v35, v0
	v_mov_b32_e32 v36, v0
	v_mov_b32_e32 v37, v0
	v_mov_b32_e32 v38, v0
	v_mov_b32_e32 v39, v0
	v_mov_b32_e32 v48, v0
	v_mov_b32_e32 v49, v0
	v_mov_b32_e32 v50, v0
	v_mov_b32_e32 v51, v0
	v_mov_b32_e32 v52, v0
	v_mov_b32_e32 v53, v0
	v_mov_b32_e32 v54, v0
	v_mov_b32_e32 v55, v0
	v_mov_b32_e32 v8, v0
	v_mov_b32_e32 v9, v0
	v_mov_b32_e32 v10, v0
	v_mov_b32_e32 v11, v0
	v_mov_b32_e32 v12, v0
	v_mov_b32_e32 v13, v0
	v_mov_b32_e32 v14, v0
	v_mov_b32_e32 v15, v0
	v_mov_b32_e32 v24, v0
	v_mov_b32_e32 v25, v0
	v_mov_b32_e32 v26, v0
	v_mov_b32_e32 v27, v0
	v_mov_b32_e32 v28, v0
	v_mov_b32_e32 v29, v0
	v_mov_b32_e32 v30, v0
	v_mov_b32_e32 v31, v0
	v_mov_b32_e32 v40, v0
	v_mov_b32_e32 v41, v0
	v_mov_b32_e32 v42, v0
	v_mov_b32_e32 v43, v0
	v_mov_b32_e32 v44, v0
	v_mov_b32_e32 v45, v0
	v_mov_b32_e32 v46, v0
	v_mov_b32_e32 v47, v0
	v_mov_b32_e32 v56, v0
	v_mov_b32_e32 v57, v0
	v_mov_b32_e32 v58, v0
	v_mov_b32_e32 v59, v0
	v_mov_b32_e32 v60, v0
	v_mov_b32_e32 v61, v0
	v_mov_b32_e32 v62, v0
	v_mov_b32_e32 v63, v0
	v_mov_b32_e32 v64, v0
	v_mov_b32_e32 v65, v0
	v_mov_b32_e32 v66, v0
	v_mov_b32_e32 v67, v0
	v_mov_b32_e32 v68, v0
	v_mov_b32_e32 v69, v0
	v_mov_b32_e32 v70, v0
	v_mov_b32_e32 v71, v0
	v_mov_b32_e32 v80, v0
	v_mov_b32_e32 v81, v0
	v_mov_b32_e32 v82, v0
	v_mov_b32_e32 v83, v0
	v_mov_b32_e32 v84, v0
	v_mov_b32_e32 v85, v0
	v_mov_b32_e32 v86, v0
	v_mov_b32_e32 v87, v0
	v_mov_b32_e32 v96, v0
	v_mov_b32_e32 v97, v0
	v_mov_b32_e32 v98, v0
	v_mov_b32_e32 v99, v0
	v_mov_b32_e32 v100, v0
	v_mov_b32_e32 v101, v0
	v_mov_b32_e32 v102, v0
	v_mov_b32_e32 v103, v0
	v_mov_b32_e32 v112, v0
	v_mov_b32_e32 v113, v0
	v_mov_b32_e32 v114, v0
	v_mov_b32_e32 v115, v0
	v_mov_b32_e32 v116, v0
	v_mov_b32_e32 v117, v0
	v_mov_b32_e32 v118, v0
	v_mov_b32_e32 v119, v0
	v_mov_b32_e32 v72, v0
	v_mov_b32_e32 v73, v0
	v_mov_b32_e32 v74, v0
	v_mov_b32_e32 v75, v0
	v_mov_b32_e32 v76, v0
	v_mov_b32_e32 v77, v0
	v_mov_b32_e32 v78, v0
	v_mov_b32_e32 v79, v0
	v_mov_b32_e32 v88, v0
	v_mov_b32_e32 v89, v0
	v_mov_b32_e32 v90, v0
	v_mov_b32_e32 v91, v0
	v_mov_b32_e32 v92, v0
	v_mov_b32_e32 v93, v0
	v_mov_b32_e32 v94, v0
	v_mov_b32_e32 v95, v0
	v_mov_b32_e32 v104, v0
	v_mov_b32_e32 v105, v0
	v_mov_b32_e32 v106, v0
	v_mov_b32_e32 v107, v0
	v_mov_b32_e32 v108, v0
	v_mov_b32_e32 v109, v0
	v_mov_b32_e32 v110, v0
	v_mov_b32_e32 v111, v0
	v_mov_b32_e32 v120, v0
	v_mov_b32_e32 v121, v0
	v_mov_b32_e32 v122, v0
	v_mov_b32_e32 v123, v0
	v_mov_b32_e32 v124, v0
	v_mov_b32_e32 v125, v0
	v_mov_b32_e32 v126, v0
	v_mov_b32_e32 v127, v0
	s_setprio 1
	s_cmp_lg_u64 s[30:31], 0
	s_cbranch_scc0 .Lprio_res
	s_setprio 0
.Lprio_res:
.LBB0_364:
	s_add_i32 s6, s74, 2
	s_add_u32 s26, s92, vcc_lo
	s_addc_u32 s27, s93, vcc_hi
	s_add_u32 s98, s26, 0x80
	s_addc_u32 s99, s27, 0
	s_add_u32 s76, s26, 0x100
	s_addc_u32 s77, s27, 0
	s_add_u32 s9, s94, vcc_lo
	s_addc_u32 s8, s95, vcc_hi
	s_add_u32 s26, s26, 0x180
	s_addc_u32 s27, s27, 0
	s_add_i32 s50, 0, 0x10000
	s_add_i32 s51, 0, 0x14000
	v_add_u32_e32 v154, s50, v168
	ds_read_b128 v[132:135], v154
	ds_read_b128 v[146:149], v154 offset:1024
	ds_read_b128 v[150:153], v154 offset:2048
	ds_read_b128 v[172:175], v154 offset:3072
	v_add_u32_e32 v154, s51, v168
	ds_read_b128 v[176:179], v154
	ds_read_b128 v[180:183], v154 offset:1024
	ds_read_b128 v[184:187], v154 offset:2048
	ds_read_b128 v[188:191], v154 offset:3072
	s_cmp_eq_u32 s5, s74
	s_cselect_b32 s74, s97, s26
	s_cselect_b32 s75, s79, s27
	s_cselect_b32 s27, s45, s8
	s_cselect_b32 s26, s96, s9
	s_cselect_b32 s77, s43, s77
	s_cselect_b32 s76, s82, s76
	s_add_i32 m0, s83, 0xc000
	ds_read_b128 v[192:195], v170
	ds_read_b128 v[196:199], v170 offset:1024
	ds_read_b128 v[200:203], v170 offset:2048
	ds_read_b128 v[208:211], v170 offset:3072
	ds_read_b128 v[214:217], v170 offset:4096
	ds_read_b128 v[230:233], v170 offset:5120
	ds_read_b128 v[234:237], v170 offset:6144
	ds_read_b128 v[238:241], v170 offset:7168
	global_load_lds_dwordx4 v144, s[98:99]
	s_add_i32 m0, s83, 0xe000
	s_nop 0
	global_load_lds_dwordx4 v142, s[98:99]
	s_waitcnt vmcnt(8)
	s_waitcnt lgkmcnt(0)
	s_barrier
; #define PG8_STAGE(bufoff, gbase, voff) do { _Pragma("unroll") for (int _i = 0; _i < 2; ++_i) \
;         __builtin_amdgcn_global_load_lds((const unsigned*)((const char*)(gbase) + (voff)[_i]), (LAS unsigned*)(lds + (bufoff) + ldsw + _i * 8192), 16, 0, 0); } while (0)
; #define PG8_LDA(dst, b, h) do { _Pragma("unroll") for (int m = 0; m < 4; ++m) _Pragma("unroll") for (int k = 0; k < 2; ++k) dst[m][k] = *(const LAS bf16x8*)(lds + PG8_SA(b, h) + aoff + m * 2048 + k * 1024); } while (0)
; #define PG8_MMA(ai, bj, At, Bt) do { __builtin_amdgcn_s_setprio(1); _Pragma("unroll") for (int m = 0; m < 4; ++m) _Pragma("unroll") for (int n = 0; n < 2; ++n) _Pragma("unroll") for (int k = 0; k < 2; ++k) \
;         acc[ai][bj][m][n] = __builtin_amdgcn_mfma_f32_16x16x32_bf16(Bt[n][k], At[m][k], acc[ai][bj][m][n], 0, 0, 0); __builtin_amdgcn_s_setprio(0); } while (0)
; #define PG8_WAIT_V(n) asm volatile("s_waitcnt vmcnt(" #n ")" ::: "memory")
; #define PG8_WAIT_L(n) asm volatile("s_waitcnt lgkmcnt(" #n ")" ::: "memory")
; #define PG8_BAR __builtin_amdgcn_s_barrier()
; #define PG8_SCHED __builtin_amdgcn_sched_barrier(0)
;     ...
;             PG8_WAIT_V(8); PG8_WAIT_L(0); PG8_BAR; PG8_MMA(0, 0, At, B0); PG8_MMA(0, 1, At, B1); PG8_BAR; PG8_SCHED;
;             PG8_LDA(At, 0, 1); PG8_STAGE(PG8_SB(0, 0), b2, voffB); PG8_STAGE(PG8_SB(0, 1), b2 + hB, voffB); PG8_STAGE(PG8_SA(0, 0), a2, voffA);
;             PG8_WAIT_V(8); PG8_WAIT_L(0); PG8_BAR; PG8_MMA(1, 0, At, B0); PG8_MMA(1, 1, At, B1); PG8_BAR; PG8_SCHED;
	s_waitcnt lgkmcnt(0)
	v_mfma_f32_16x16x32_bf16 v[124:127], v[132:135], v[192:195], v[124:127]
	v_mfma_f32_16x16x32_bf16 v[124:127], v[146:149], v[196:199], v[124:127]
	v_mfma_f32_16x16x32_bf16 v[120:123], v[172:175], v[196:199], v[120:123]
	v_mfma_f32_16x16x32_bf16 v[120:123], v[150:153], v[192:195], v[120:123]
	v_mfma_f32_16x16x32_bf16 v[104:107], v[150:153], v[200:203], v[104:107]
	v_mfma_f32_16x16x32_bf16 v[104:107], v[172:175], v[208:211], v[104:107]
	v_mfma_f32_16x16x32_bf16 v[108:111], v[146:149], v[208:211], v[108:111]
	v_mfma_f32_16x16x32_bf16 v[108:111], v[132:135], v[200:203], v[108:111]
	v_mfma_f32_16x16x32_bf16 v[92:95], v[132:135], v[214:217], v[92:95]
	v_mfma_f32_16x16x32_bf16 v[92:95], v[146:149], v[230:233], v[92:95]
	v_mfma_f32_16x16x32_bf16 v[88:91], v[172:175], v[230:233], v[88:91]
	v_mfma_f32_16x16x32_bf16 v[88:91], v[150:153], v[214:217], v[88:91]
	v_mfma_f32_16x16x32_bf16 v[72:75], v[150:153], v[234:237], v[72:75]
	v_mfma_f32_16x16x32_bf16 v[72:75], v[172:175], v[238:241], v[72:75]
	v_mfma_f32_16x16x32_bf16 v[76:79], v[146:149], v[238:241], v[76:79]
	v_mfma_f32_16x16x32_bf16 v[76:79], v[132:135], v[234:237], v[76:79]
	v_mfma_f32_16x16x32_bf16 v[116:119], v[176:179], v[192:195], v[116:119]
	v_mfma_f32_16x16x32_bf16 v[116:119], v[180:183], v[196:199], v[116:119]
	v_mfma_f32_16x16x32_bf16 v[112:115], v[188:191], v[196:199], v[112:115]
	v_mfma_f32_16x16x32_bf16 v[112:115], v[184:187], v[192:195], v[112:115]
	v_mfma_f32_16x16x32_bf16 v[96:99], v[184:187], v[200:203], v[96:99]
	v_mfma_f32_16x16x32_bf16 v[96:99], v[188:191], v[208:211], v[96:99]
	v_mfma_f32_16x16x32_bf16 v[100:103], v[180:183], v[208:211], v[100:103]
	v_mfma_f32_16x16x32_bf16 v[100:103], v[176:179], v[200:203], v[100:103]
	v_mfma_f32_16x16x32_bf16 v[84:87], v[176:179], v[214:217], v[84:87]
	v_mfma_f32_16x16x32_bf16 v[84:87], v[180:183], v[230:233], v[84:87]
	v_mfma_f32_16x16x32_bf16 v[80:83], v[188:191], v[230:233], v[80:83]
	v_mfma_f32_16x16x32_bf16 v[80:83], v[184:187], v[214:217], v[80:83]
	v_mfma_f32_16x16x32_bf16 v[64:67], v[184:187], v[234:237], v[64:67]
	v_mfma_f32_16x16x32_bf16 v[64:67], v[188:191], v[238:241], v[64:67]
	v_mfma_f32_16x16x32_bf16 v[68:71], v[180:183], v[238:241], v[68:71]
	v_mfma_f32_16x16x32_bf16 v[68:71], v[176:179], v[234:237], v[68:71]
	s_barrier
	s_add_i32 s8, s50, s81
	s_mov_b32 m0, s8
	ds_read_b128 v[192:195], v170 offset:16384
	ds_read_b128 v[196:199], v170 offset:17408
	ds_read_b128 v[200:203], v170 offset:18432
	ds_read_b128 v[208:211], v170 offset:19456
	ds_read_b128 v[214:217], v170 offset:20480
	ds_read_b128 v[230:233], v170 offset:21504
	ds_read_b128 v[234:237], v170 offset:22528
	ds_read_b128 v[238:241], v170 offset:23552
	global_load_lds_dwordx4 v156, s[26:27]
	s_add_i32 m0, s8, 0x2000
	s_mov_b64 s[100:101], s[26:27]
	s_add_u32 s26, s26, s16
	s_addc_u32 s27, s27, 0
	s_add_i32 s8, s51, s81
	global_load_lds_dwordx4 v140, s[100:101]
	s_mov_b32 m0, s8
	s_nop 0
	global_load_lds_dwordx4 v156, s[26:27]
	s_add_i32 m0, s8, 0x2000
	s_nop 0
	global_load_lds_dwordx4 v140, s[26:27]
	s_mov_b32 m0, s83
	s_nop 0
	global_load_lds_dwordx4 v136, s[76:77]
	s_mov_b32 m0, s2
	s_nop 0
	global_load_lds_dwordx4 v138, s[76:77]
	s_waitcnt vmcnt(8)
	s_waitcnt lgkmcnt(0)
	s_barrier
	s_waitcnt lgkmcnt(0)
	v_mfma_f32_16x16x32_bf16 v[60:63], v[132:135], v[192:195], v[60:63]
	v_mfma_f32_16x16x32_bf16 v[60:63], v[146:149], v[196:199], v[60:63]
	v_mfma_f32_16x16x32_bf16 v[56:59], v[172:175], v[196:199], v[56:59]
	v_mfma_f32_16x16x32_bf16 v[56:59], v[150:153], v[192:195], v[56:59]
	v_mfma_f32_16x16x32_bf16 v[40:43], v[150:153], v[200:203], v[40:43]
	v_mfma_f32_16x16x32_bf16 v[40:43], v[172:175], v[208:211], v[40:43]
	v_mfma_f32_16x16x32_bf16 v[44:47], v[146:149], v[208:211], v[44:47]
	v_mfma_f32_16x16x32_bf16 v[44:47], v[132:135], v[200:203], v[44:47]
	v_mfma_f32_16x16x32_bf16 v[28:31], v[132:135], v[214:217], v[28:31]
	v_mfma_f32_16x16x32_bf16 v[28:31], v[146:149], v[230:233], v[28:31]
	v_mfma_f32_16x16x32_bf16 v[24:27], v[172:175], v[230:233], v[24:27]
	v_mfma_f32_16x16x32_bf16 v[24:27], v[150:153], v[214:217], v[24:27]
	v_mfma_f32_16x16x32_bf16 v[8:11], v[150:153], v[234:237], v[8:11]
	v_mfma_f32_16x16x32_bf16 v[8:11], v[172:175], v[238:241], v[8:11]
	v_mfma_f32_16x16x32_bf16 v[12:15], v[146:149], v[238:241], v[12:15]
	v_mfma_f32_16x16x32_bf16 v[12:15], v[132:135], v[234:237], v[12:15]
	v_mfma_f32_16x16x32_bf16 v[52:55], v[176:179], v[192:195], v[52:55]
	v_mfma_f32_16x16x32_bf16 v[52:55], v[180:183], v[196:199], v[52:55]
	v_mfma_f32_16x16x32_bf16 v[48:51], v[188:191], v[196:199], v[48:51]
	v_mfma_f32_16x16x32_bf16 v[48:51], v[184:187], v[192:195], v[48:51]
	v_mfma_f32_16x16x32_bf16 v[32:35], v[184:187], v[200:203], v[32:35]
	v_mfma_f32_16x16x32_bf16 v[32:35], v[188:191], v[208:211], v[32:35]
	v_mfma_f32_16x16x32_bf16 v[36:39], v[180:183], v[208:211], v[36:39]
	v_mfma_f32_16x16x32_bf16 v[36:39], v[176:179], v[200:203], v[36:39]
	v_mfma_f32_16x16x32_bf16 v[20:23], v[176:179], v[214:217], v[20:23]
	v_mfma_f32_16x16x32_bf16 v[20:23], v[180:183], v[230:233], v[20:23]
	v_mfma_f32_16x16x32_bf16 v[16:19], v[188:191], v[230:233], v[16:19]
	v_mfma_f32_16x16x32_bf16 v[16:19], v[184:187], v[214:217], v[16:19]
	v_mfma_f32_16x16x32_bf16 v[0:3], v[184:187], v[234:237], v[0:3]
	v_mfma_f32_16x16x32_bf16 v[0:3], v[188:191], v[238:241], v[0:3]
	v_mfma_f32_16x16x32_bf16 v[4:7], v[180:183], v[238:241], v[4:7]
	v_mfma_f32_16x16x32_bf16 v[4:7], v[176:179], v[234:237], v[4:7]
	s_barrier
; #define PG8_STAGE(bufoff, gbase, voff) do { _Pragma("unroll") for (int _i = 0; _i < 2; ++_i) \
;         __builtin_amdgcn_global_load_lds((const unsigned*)((const char*)(gbase) + (voff)[_i]), (LAS unsigned*)(lds + (bufoff) + ldsw + _i * 8192), 16, 0, 0); } while (0)
; #define PG8_LDA(dst, b, h) do { _Pragma("unroll") for (int m = 0; m < 4; ++m) _Pragma("unroll") for (int k = 0; k < 2; ++k) dst[m][k] = *(const LAS bf16x8*)(lds + PG8_SA(b, h) + aoff + m * 2048 + k * 1024); } while (0)
; #define PG8_BAR __builtin_amdgcn_s_barrier()
;     ...
;             PG8_LDB(B0, 1, 0); PG8_LDB(B1, 1, 1); PG8_SCHED; PG8_LDA(At, 1, 0); PG8_STAGE(PG8_SA(0, 1), a2 + hA, voffA);
;             PG8_WAIT_V(8); PG8_WAIT_L(0); PG8_BAR; PG8_MMA(0, 0, At, B0); PG8_MMA(0, 1, At, B1); PG8_BAR; PG8_SCHED;
;             PG8_LDA(At, 1, 1); PG8_STAGE(PG8_SB(1, 0), b3, voffB); PG8_STAGE(PG8_SB(1, 1), b3 + hB, voffB); PG8_STAGE(PG8_SA(1, 0), a3, voffA);
;             PG8_WAIT_V(8); PG8_WAIT_L(0); PG8_BAR; PG8_MMA(1, 0, At, B0); PG8_MMA(1, 1, At, B1); PG8_BAR; PG8_SCHED;
;             } else {
;             PG8_LDB(B0, 0, 0); PG8_SCHED; PG8_LDA(At, 0, 0); PG8_STAGE(PG8_SA(1, 1), a1 + hA, voffA);
;             PG8_WAIT_L(8); PG8_BAR; PG8_WAIT_L(0); PG8_MMA(0, 0, At, B0); PG8_BAR; PG8_SCHED;
;             PG8_LDB(B1, 0, 1); PG8_STAGE(PG8_SB(0, 0), b2, voffB);
;             PG8_BAR; PG8_WAIT_L(0); PG8_MMA(0, 1, At, B1); PG8_BAR;
;             PG8_LDA(At, 0, 1); PG8_STAGE(PG8_SA(0, 0), a2, voffA);
;             PG8_BAR; PG8_WAIT_L(0); PG8_MMA(1, 0, At, B0); PG8_BAR; PG8_SCHED;
;             PG8_STAGE(PG8_SB(0, 1), b2 + hB, voffB);
;             PG8_WAIT_V(6); PG8_BAR; PG8_MMA(1, 1, At, B1); PG8_BAR;
;             PG8_LDB(B0, 1, 0); PG8_SCHED; PG8_LDA(At, 1, 0); PG8_STAGE(PG8_SA(0, 1), a2 + hA, voffA);
;             PG8_WAIT_L(8); PG8_BAR; PG8_WAIT_L(0); PG8_MMA(0, 0, At, B0); PG8_BAR; PG8_SCHED;
;             PG8_LDB(B1, 1, 1); PG8_STAGE(PG8_SB(1, 0), b3, voffB);
;             PG8_BAR; PG8_WAIT_L(0); PG8_MMA(0, 1, At, B1); PG8_BAR;
;             PG8_LDA(At, 1, 1); PG8_STAGE(PG8_SA(1, 0), a3, voffA);
;             PG8_BAR; PG8_WAIT_L(0); PG8_MMA(1, 0, At, B0); PG8_BAR; PG8_SCHED;
;             PG8_STAGE(PG8_SB(1, 1), b3 + hB, voffB);
;             PG8_WAIT_V(6); PG8_BAR; PG8_MMA(1, 1, At, B1); PG8_BAR;
;             }
;         }
;         if constexpr (ALIGN_EPI) { if (wr == 0) PG8_BAR; }
	s_add_i32 s8, 0, 0x18000
	v_add_u32_e32 v171, s8, v168
	s_add_i32 s9, 0, 0x1c000
	ds_read_b128 v[132:135], v171
	ds_read_b128 v[146:149], v171 offset:1024
	ds_read_b128 v[150:153], v171 offset:2048
	ds_read_b128 v[172:175], v171 offset:3072
	v_add_u32_e32 v171, s9, v168
	ds_read_b128 v[176:179], v171
	ds_read_b128 v[180:183], v171 offset:1024
	ds_read_b128 v[184:187], v171 offset:2048
	ds_read_b128 v[188:191], v171 offset:3072
	s_add_u32 s26, s76, s16
	s_addc_u32 s27, s77, 0
	s_mov_b32 m0, s3
	ds_read_b128 v[192:195], v170 offset:32768
	ds_read_b128 v[196:199], v170 offset:33792
	ds_read_b128 v[200:203], v170 offset:34816
	ds_read_b128 v[208:211], v170 offset:35840
	ds_read_b128 v[214:217], v170 offset:36864
	ds_read_b128 v[230:233], v170 offset:37888
	ds_read_b128 v[234:237], v170 offset:38912
	ds_read_b128 v[238:241], v170 offset:39936
	global_load_lds_dwordx4 v136, s[26:27]
	s_mov_b32 m0, s0
	s_nop 0
	global_load_lds_dwordx4 v138, s[26:27]
	s_waitcnt vmcnt(8)
	s_waitcnt lgkmcnt(0)
	s_barrier
	s_waitcnt lgkmcnt(0)
	v_mfma_f32_16x16x32_bf16 v[124:127], v[132:135], v[192:195], v[124:127]
	v_mfma_f32_16x16x32_bf16 v[124:127], v[146:149], v[196:199], v[124:127]
	v_mfma_f32_16x16x32_bf16 v[120:123], v[172:175], v[196:199], v[120:123]
	v_mfma_f32_16x16x32_bf16 v[120:123], v[150:153], v[192:195], v[120:123]
	v_mfma_f32_16x16x32_bf16 v[104:107], v[150:153], v[200:203], v[104:107]
	v_mfma_f32_16x16x32_bf16 v[104:107], v[172:175], v[208:211], v[104:107]
	v_mfma_f32_16x16x32_bf16 v[108:111], v[146:149], v[208:211], v[108:111]
	v_mfma_f32_16x16x32_bf16 v[108:111], v[132:135], v[200:203], v[108:111]
	v_mfma_f32_16x16x32_bf16 v[92:95], v[132:135], v[214:217], v[92:95]
	v_mfma_f32_16x16x32_bf16 v[92:95], v[146:149], v[230:233], v[92:95]
	v_mfma_f32_16x16x32_bf16 v[88:91], v[172:175], v[230:233], v[88:91]
	v_mfma_f32_16x16x32_bf16 v[88:91], v[150:153], v[214:217], v[88:91]
	v_mfma_f32_16x16x32_bf16 v[72:75], v[150:153], v[234:237], v[72:75]
	v_mfma_f32_16x16x32_bf16 v[72:75], v[172:175], v[238:241], v[72:75]
	v_mfma_f32_16x16x32_bf16 v[76:79], v[146:149], v[238:241], v[76:79]
	v_mfma_f32_16x16x32_bf16 v[76:79], v[132:135], v[234:237], v[76:79]
	v_mfma_f32_16x16x32_bf16 v[116:119], v[176:179], v[192:195], v[116:119]
	v_mfma_f32_16x16x32_bf16 v[116:119], v[180:183], v[196:199], v[116:119]
	v_mfma_f32_16x16x32_bf16 v[112:115], v[188:191], v[196:199], v[112:115]
	v_mfma_f32_16x16x32_bf16 v[112:115], v[184:187], v[192:195], v[112:115]
	v_mfma_f32_16x16x32_bf16 v[96:99], v[184:187], v[200:203], v[96:99]
	v_mfma_f32_16x16x32_bf16 v[96:99], v[188:191], v[208:211], v[96:99]
	v_mfma_f32_16x16x32_bf16 v[100:103], v[180:183], v[208:211], v[100:103]
	v_mfma_f32_16x16x32_bf16 v[100:103], v[176:179], v[200:203], v[100:103]
	v_mfma_f32_16x16x32_bf16 v[84:87], v[176:179], v[214:217], v[84:87]
	v_mfma_f32_16x16x32_bf16 v[84:87], v[180:183], v[230:233], v[84:87]
	v_mfma_f32_16x16x32_bf16 v[80:83], v[188:191], v[230:233], v[80:83]
	v_mfma_f32_16x16x32_bf16 v[80:83], v[184:187], v[214:217], v[80:83]
	v_mfma_f32_16x16x32_bf16 v[64:67], v[184:187], v[234:237], v[64:67]
	v_mfma_f32_16x16x32_bf16 v[64:67], v[188:191], v[238:241], v[64:67]
	v_mfma_f32_16x16x32_bf16 v[68:71], v[180:183], v[238:241], v[68:71]
	v_mfma_f32_16x16x32_bf16 v[68:71], v[176:179], v[234:237], v[68:71]
	s_barrier
	s_add_i32 s8, s8, s81
	s_add_u32 s98, s100, s38
	s_addc_u32 s99, s101, s39
	s_add_u32 s100, s98, s16
	s_addc_u32 s101, s99, 0
	s_mov_b32 m0, s8
	ds_read_b128 v[192:195], v170 offset:49152
	ds_read_b128 v[196:199], v170 offset:50176
	ds_read_b128 v[200:203], v170 offset:51200
	ds_read_b128 v[208:211], v170 offset:52224
	ds_read_b128 v[214:217], v170 offset:53248
	ds_read_b128 v[230:233], v170 offset:54272
	ds_read_b128 v[234:237], v170 offset:55296
	ds_read_b128 v[238:241], v170 offset:56320
	global_load_lds_dwordx4 v156, s[98:99]
	s_add_i32 m0, s8, 0x2000
	s_add_i32 s8, s9, s81
	global_load_lds_dwordx4 v140, s[98:99]
	s_mov_b32 m0, s8
	s_nop 0
	global_load_lds_dwordx4 v156, s[100:101]
	s_add_i32 m0, s8, 0x2000
	s_nop 0
	global_load_lds_dwordx4 v140, s[100:101]
	s_mov_b32 m0, s1
	s_nop 0
	global_load_lds_dwordx4 v136, s[74:75]
	s_mov_b32 m0, s54
	s_nop 0
	global_load_lds_dwordx4 v138, s[74:75]
	s_waitcnt vmcnt(8)
	s_waitcnt lgkmcnt(0)
	s_barrier
	s_waitcnt lgkmcnt(0)
	v_mfma_f32_16x16x32_bf16 v[60:63], v[132:135], v[192:195], v[60:63]
	v_mfma_f32_16x16x32_bf16 v[60:63], v[146:149], v[196:199], v[60:63]
	v_mfma_f32_16x16x32_bf16 v[56:59], v[172:175], v[196:199], v[56:59]
	v_mfma_f32_16x16x32_bf16 v[56:59], v[150:153], v[192:195], v[56:59]
	v_mfma_f32_16x16x32_bf16 v[40:43], v[150:153], v[200:203], v[40:43]
	v_mfma_f32_16x16x32_bf16 v[40:43], v[172:175], v[208:211], v[40:43]
	v_mfma_f32_16x16x32_bf16 v[44:47], v[146:149], v[208:211], v[44:47]
	v_mfma_f32_16x16x32_bf16 v[44:47], v[132:135], v[200:203], v[44:47]
	v_mfma_f32_16x16x32_bf16 v[28:31], v[132:135], v[214:217], v[28:31]
	v_mfma_f32_16x16x32_bf16 v[28:31], v[146:149], v[230:233], v[28:31]
	v_mfma_f32_16x16x32_bf16 v[24:27], v[172:175], v[230:233], v[24:27]
	v_mfma_f32_16x16x32_bf16 v[24:27], v[150:153], v[214:217], v[24:27]
	v_mfma_f32_16x16x32_bf16 v[8:11], v[150:153], v[234:237], v[8:11]
	v_mfma_f32_16x16x32_bf16 v[8:11], v[172:175], v[238:241], v[8:11]
	v_mfma_f32_16x16x32_bf16 v[12:15], v[146:149], v[238:241], v[12:15]
	v_mfma_f32_16x16x32_bf16 v[12:15], v[132:135], v[234:237], v[12:15]
	v_mfma_f32_16x16x32_bf16 v[52:55], v[176:179], v[192:195], v[52:55]
	v_mfma_f32_16x16x32_bf16 v[52:55], v[180:183], v[196:199], v[52:55]
	v_mfma_f32_16x16x32_bf16 v[48:51], v[188:191], v[196:199], v[48:51]
	v_mfma_f32_16x16x32_bf16 v[48:51], v[184:187], v[192:195], v[48:51]
	v_mfma_f32_16x16x32_bf16 v[32:35], v[184:187], v[200:203], v[32:35]
	v_mfma_f32_16x16x32_bf16 v[32:35], v[188:191], v[208:211], v[32:35]
	v_mfma_f32_16x16x32_bf16 v[36:39], v[180:183], v[208:211], v[36:39]
	v_mfma_f32_16x16x32_bf16 v[36:39], v[176:179], v[200:203], v[36:39]
	v_mfma_f32_16x16x32_bf16 v[20:23], v[176:179], v[214:217], v[20:23]
	v_mfma_f32_16x16x32_bf16 v[20:23], v[180:183], v[230:233], v[20:23]
	v_mfma_f32_16x16x32_bf16 v[16:19], v[188:191], v[230:233], v[16:19]
	v_mfma_f32_16x16x32_bf16 v[16:19], v[184:187], v[214:217], v[16:19]
	v_mfma_f32_16x16x32_bf16 v[0:3], v[184:187], v[234:237], v[0:3]
	v_mfma_f32_16x16x32_bf16 v[0:3], v[188:191], v[238:241], v[0:3]
	v_mfma_f32_16x16x32_bf16 v[4:7], v[180:183], v[238:241], v[4:7]
	v_mfma_f32_16x16x32_bf16 v[4:7], v[176:179], v[234:237], v[4:7]
	s_barrier
	s_add_u32 vcc_lo, vcc_lo, 0x100
	s_addc_u32 vcc_hi, vcc_hi, 0
	s_cmp_ge_u32 s6, s4
	s_mov_b32 s74, s6
	s_cbranch_scc0 .LBB0_364
	s_and_b64 vcc, exec, s[30:31]
	s_cbranch_vccz .LBB0_367
	s_barrier
; __device__ __forceinline__ float bflo(unsigned w) { return __uint_as_float(w << 16); }
; __device__ __forceinline__ float bfhi(unsigned w) { return __uint_as_float(w & 0xffff0000u); }
; __device__ __forceinline__ u32x4 pack8(f32x4 v0, f32x4 v1) { u32x4 w; w.x = cvt_pk_bf16(v0[0], v0[1]); w.y = cvt_pk_bf16(v0[2], v0[3]); w.z = cvt_pk_bf16(v1[0], v1[1]); w.w = cvt_pk_bf16(v1[2], v1[3]); return w; }
;     __device__ __forceinline__ void operator()(EPI_ARGS) const {
;         const int row0 = u.om * BM + wr * 64 + fr, col0 = u.on * BM + wc * 32 + 8 * fq;
;         u32x4 xn0 = gld16(xb + (size_t)row0 * D + col0), xn1 = gld16(xb + (size_t)row0 * D + col0 + HALF);
; #pragma unroll
;         for (int idx = 0; idx < 8; ++idx) { const int ai = idx >> 2, m = idx & 3, row = row0 + ai * HALF + m * 16; const u32x4 xc[2] = {xn0, xn1}; float sq = 0.f;
;             if (idx < 7) { const int rn = row0 + ((idx + 1) >> 2) * HALF + ((idx + 1) & 3) * 16; xn0 = gld16(xb + (size_t)rn * D + col0); xn1 = gld16(xb + (size_t)rn * D + col0 + HALF); }
; #pragma unroll
;             for (int bj = 0; bj < 2; ++bj) { const size_t off = (size_t)row * D + col0 + bj * HALF; const u32x4 xo = xc[bj];
;                 f32x4 v0 = acc[ai][bj][m][0], v1 = acc[ai][bj][m][1];
;                 v0[0] += bflo(xo.x); v0[1] += bfhi(xo.x); v0[2] += bflo(xo.y); v0[3] += bfhi(xo.y); v1[0] += bflo(xo.z); v1[1] += bfhi(xo.z); v1[2] += bflo(xo.w); v1[3] += bfhi(xo.w);
;                 const u32x4 w = pack8(v0, v1); gst16(xb + off, w);
;                 const float r0 = bflo(w.x), r1 = bfhi(w.x), r2 = bflo(w.y), r3 = bfhi(w.y), r4 = bflo(w.z), r5 = bfhi(w.z), r6 = bflo(w.w), r7 = bfhi(w.w);
;                 sq += (r0 * r0 + r1 * r1) + (r2 * r2 + r3 * r3) + (r4 * r4 + r5 * r5) + (r6 * r6 + r7 * r7); }
;             sq = red4(sq);
;             if (fq == 0) gstf(ssn + (size_t)row * 16 + u.on * 4 + wc, sq); }
.LBB0_367:
	s_setprio 0
	v_lshl_add_u32 v148, s55, 8, v165
	v_lshl_or_b32 v146, s7, 8, v169
	v_ashrrev_i32_e32 v149, 31, v148
	v_lshlrev_b64 v[128:129], 11, v[148:149]
	v_ashrrev_i32_e32 v147, 31, v146
	v_lshl_add_u64 v[128:129], s[46:47], 0, v[128:129]
	v_lshlrev_b64 v[130:131], 1, v[146:147]
	v_lshl_add_u64 v[154:155], v[128:129], 0, v[130:131]
	global_load_dwordx4 v[172:175], v[154:155], off
	global_load_dwordx4 v[176:179], v[154:155], off offset:256
	v_or_b32_e32 v150, 16, v148
	v_ashrrev_i32_e32 v151, 31, v150
	v_lshlrev_b64 v[128:129], 11, v[150:151]
	v_lshl_add_u64 v[128:129], s[46:47], 0, v[128:129]
	v_lshl_add_u64 v[152:153], v[128:129], 0, v[130:131]
	global_load_dwordx4 v[132:135], v[152:153], off
	global_load_dwordx4 v[128:131], v[152:153], off offset:256
	s_lshl_b32 s92, s7, 2
	s_ashr_i32 s93, s92, 31
	s_waitcnt vmcnt(0)
	v_lshlrev_b32_e32 v171, 16, v172
	v_add_f32_e32 v124, v124, v171
	v_and_b32_e32 v171, 0xffff0000, v172
	v_add_f32_e32 v125, v125, v171
	v_lshlrev_b32_e32 v171, 16, v173
	v_add_f32_e32 v126, v126, v171
	v_and_b32_e32 v171, 0xffff0000, v173
	v_add_f32_e32 v127, v127, v171
	v_lshlrev_b32_e32 v171, 16, v174
	v_add_f32_e32 v171, v120, v171
	v_and_b32_e32 v120, 0xffff0000, v174
	v_add_f32_e32 v172, v121, v120
	v_lshlrev_b32_e32 v120, 16, v175
	v_add_f32_e32 v173, v122, v120
	v_and_b32_e32 v120, 0xffff0000, v175
	v_add_f32_e32 v123, v123, v120
	v_cvt_pk_bf16_f32 v120, v124, v125
	v_cvt_pk_bf16_f32 v121, v126, v127
	v_cvt_pk_bf16_f32 v122, v171, v172
	v_cvt_pk_bf16_f32 v123, v173, v123
	global_store_dwordx4 v[154:155], v[120:123], off
	v_lshlrev_b32_e32 v124, 16, v120
	v_lshlrev_b32_e32 v125, 16, v121
	v_and_b32_e32 v120, 0xffff0000, v120
	v_and_b32_e32 v121, 0xffff0000, v121
	v_mul_f32_e32 v120, v120, v120
	v_mul_f32_e32 v121, v121, v121
	v_lshlrev_b32_e32 v126, 16, v122
	v_and_b32_e32 v122, 0xffff0000, v122
	v_fmac_f32_e32 v120, v124, v124
	v_fmac_f32_e32 v121, v125, v125
	v_add_f32_e32 v120, v120, v121
	v_mul_f32_e32 v121, v122, v122
	v_lshlrev_b32_e32 v127, 16, v123
	v_and_b32_e32 v123, 0xffff0000, v123
	v_fmac_f32_e32 v121, v126, v126
	v_add_f32_e32 v120, v120, v121
	v_mul_f32_e32 v121, v123, v123
	v_fmac_f32_e32 v121, v127, v127
	v_add_f32_e32 v120, v120, v121
	v_lshlrev_b32_e32 v121, 16, v176
	v_add_f32_e32 v116, v116, v121
	v_and_b32_e32 v121, 0xffff0000, v176
	v_add_f32_e32 v117, v117, v121
	v_lshlrev_b32_e32 v121, 16, v177
	v_add_f32_e32 v118, v118, v121
	v_and_b32_e32 v121, 0xffff0000, v177
	v_add_f32_e32 v119, v119, v121
	v_lshlrev_b32_e32 v121, 16, v178
	v_add_f32_e32 v121, v112, v121
	v_and_b32_e32 v112, 0xffff0000, v178
	v_add_f32_e32 v122, v113, v112
	v_lshlrev_b32_e32 v112, 16, v179
	v_add_f32_e32 v123, v114, v112
	v_and_b32_e32 v112, 0xffff0000, v179
	v_add_f32_e32 v115, v115, v112
	v_cvt_pk_bf16_f32 v112, v116, v117
	v_cvt_pk_bf16_f32 v113, v118, v119
	v_cvt_pk_bf16_f32 v114, v121, v122
	v_cvt_pk_bf16_f32 v115, v123, v115
	global_store_dwordx4 v[154:155], v[112:115], off offset:256
	v_lshlrev_b32_e32 v116, 16, v112
	v_lshlrev_b32_e32 v117, 16, v113
	v_and_b32_e32 v112, 0xffff0000, v112
	v_and_b32_e32 v113, 0xffff0000, v113
	v_mul_f32_e32 v112, v112, v112
	v_mul_f32_e32 v113, v113, v113
	v_lshlrev_b32_e32 v118, 16, v114
	v_and_b32_e32 v114, 0xffff0000, v114
	v_fmac_f32_e32 v112, v116, v116
	v_fmac_f32_e32 v113, v117, v117
	v_add_f32_e32 v112, v112, v113
	v_mul_f32_e32 v113, v114, v114
	v_lshlrev_b32_e32 v119, 16, v115
	v_and_b32_e32 v115, 0xffff0000, v115
	v_fmac_f32_e32 v113, v118, v118
	v_add_f32_e32 v112, v112, v113
	v_mul_f32_e32 v113, v115, v115
	v_fmac_f32_e32 v113, v119, v119
	v_add_f32_e32 v112, v112, v113
	v_add_f32_e32 v112, v120, v112
	v_mov_b32_e32 v113, v112
	s_nop 1
	v_permlane16_swap_b32_e32 v112, v113
	v_add_f32_e32 v112, v112, v113
	v_mov_b32_e32 v113, v112
	s_nop 1
	v_permlane32_swap_b32_e32 v112, v113
	s_and_saveexec_b64 s[74:75], s[40:41]
	s_movk_i32 s96, 0x300
	s_movk_i32 s97, 0xfe80
	s_cbranch_execz .LBB0_369
	v_add_f32_e32 v114, v112, v113
	v_lshlrev_b64 v[112:113], 6, v[148:149]
	v_lshl_add_u64 v[112:113], s[28:29], 0, v[112:113]
	v_lshl_add_u64 v[112:113], s[92:93], 2, v[112:113]
	s_lshl_b32 s6, s36, 2
	s_mov_b32 s7, s88
	v_lshl_add_u64 v[112:113], v[112:113], 0, s[6:7]
	global_store_dword v[112:113], v114, off
